# GEMM K-loops: LDS-DMA loads use SGPR base + 32-bit VGPR offset (no per-load 64-bit VALU add), all four GEMMs (stacked)
# baseline (speedup 1.0000x reference)
.LBB0_162:
	s_ashr_i32 s29, s28, 31
	s_lshl_b64 s[30:31], s[28:29], 19
	s_add_u32 s30, s62, s30
	s_addc_u32 s31, s63, s31
	s_and_b64 s[34:35], s[36:37], exec
	s_cselect_b32 s29, s31, s43
	s_cselect_b32 s60, s30, s42
	s_ashr_i32 s27, s26, 31
	s_lshl_b64 s[34:35], s[26:27], 19
	s_add_u32 s34, s17, s34
	s_addc_u32 s35, s18, s35
	s_and_b64 s[44:45], s[36:37], exec
	s_cselect_b32 s27, s35, s41
	s_cselect_b32 s61, s34, s40
	s_lshl_b32 s3, s38, 8
	v_add_u32_e32 v0, s3, v141
	s_add_u32 s64, s40, 0x100
	v_ashrrev_i32_e32 v1, 31, v0
	s_addc_u32 s65, s41, 0
	v_lshl_add_u64 v[156:157], v[0:1], 2, s[72:73]
	s_add_u32 s38, s42, 0xa000
	v_mov_b32_e32 v0, 0
	s_addc_u32 s39, s43, 0
	s_mov_b32 s66, -2
	s_mov_b64 s[40:41], 0
	s_add_u32 s42, s38, 0x6000
	s_addc_u32 s43, s39, 0
	s_and_b64 s[40:41], s[40:41], exec
	s_cselect_b32 s44, s60, s42
	s_cselect_b32 s45, s29, s43
	s_cselect_b32 s43, s27, s65
	s_cselect_b32 s42, s61, s64
	s_add_u32 s40, s44, 0x8000
	s_addc_u32 s41, s45, 0
	s_add_i32 s67, 0, 0x10000
	v_add_u32_e32 v159, s67, v143
	s_add_i32 s70, 0, 0x14000
	ds_read_b128 v[160:163], v159
	ds_read_b128 v[164:167], v159 offset:1024
	ds_read_b128 v[168:171], v159 offset:2048
	ds_read_b128 v[172:175], v159 offset:3072
	v_add_u32_e32 v159, s70, v143
	ds_read_b128 v[176:179], v159
	ds_read_b128 v[180:183], v159 offset:1024
	ds_read_b128 v[184:187], v159 offset:2048
	ds_read_b128 v[188:191], v159 offset:3072
	s_add_i32 m0, s46, 0xc000
	ds_read_b128 v[192:195], v153
	ds_read_b128 v[196:199], v153 offset:1024
	ds_read_b128 v[200:203], v153 offset:2048
	ds_read_b128 v[204:207], v153 offset:3072
	ds_read_b128 v[218:221], v153 offset:4096
	ds_read_b128 v[222:225], v153 offset:5120
	ds_read_b128 v[226:229], v153 offset:6144
	ds_read_b128 v[230:233], v153 offset:7168
	global_load_lds_dwordx4 v136, s[38:39]
	s_add_i32 m0, s46, 0xe000
	s_nop 0
	global_load_lds_dwordx4 v138, s[38:39]
	s_waitcnt vmcnt(8)
	s_waitcnt lgkmcnt(0)
	s_barrier
	s_setprio 1
	s_waitcnt lgkmcnt(0)
	v_mfma_f32_16x16x32_bf16 v[124:127], v[160:163], v[192:195], 0
	v_mfma_f32_16x16x32_bf16 v[120:123], v[168:171], v[192:195], 0
	v_mfma_f32_16x16x32_bf16 v[108:111], v[160:163], v[200:203], 0
	v_mfma_f32_16x16x32_bf16 v[104:107], v[168:171], v[200:203], 0
	v_mfma_f32_16x16x32_bf16 v[92:95], v[160:163], v[218:221], 0
	v_mfma_f32_16x16x32_bf16 v[88:91], v[168:171], v[218:221], 0
	v_mfma_f32_16x16x32_bf16 v[76:79], v[160:163], v[226:229], 0
	v_mfma_f32_16x16x32_bf16 v[72:75], v[168:171], v[226:229], 0
	v_mfma_f32_16x16x32_bf16 v[124:127], v[164:167], v[196:199], v[124:127]
	v_mfma_f32_16x16x32_bf16 v[120:123], v[172:175], v[196:199], v[120:123]
	v_mfma_f32_16x16x32_bf16 v[108:111], v[164:167], v[204:207], v[108:111]
	v_mfma_f32_16x16x32_bf16 v[104:107], v[172:175], v[204:207], v[104:107]
	v_mfma_f32_16x16x32_bf16 v[92:95], v[164:167], v[222:225], v[92:95]
	v_mfma_f32_16x16x32_bf16 v[88:91], v[172:175], v[222:225], v[88:91]
	v_mfma_f32_16x16x32_bf16 v[76:79], v[164:167], v[230:233], v[76:79]
	v_mfma_f32_16x16x32_bf16 v[72:75], v[172:175], v[230:233], v[72:75]
	s_setprio 0
	s_setprio 1
	v_mfma_f32_16x16x32_bf16 v[116:119], v[176:179], v[192:195], 0
	v_mfma_f32_16x16x32_bf16 v[112:115], v[184:187], v[192:195], 0
	v_mfma_f32_16x16x32_bf16 v[100:103], v[176:179], v[200:203], 0
	v_mfma_f32_16x16x32_bf16 v[96:99], v[184:187], v[200:203], 0
	v_mfma_f32_16x16x32_bf16 v[84:87], v[176:179], v[218:221], 0
	v_mfma_f32_16x16x32_bf16 v[80:83], v[184:187], v[218:221], 0
	v_mfma_f32_16x16x32_bf16 v[68:71], v[176:179], v[226:229], 0
	v_mfma_f32_16x16x32_bf16 v[64:67], v[184:187], v[226:229], 0
	v_mfma_f32_16x16x32_bf16 v[116:119], v[180:183], v[196:199], v[116:119]
	v_mfma_f32_16x16x32_bf16 v[112:115], v[188:191], v[196:199], v[112:115]
	v_mfma_f32_16x16x32_bf16 v[100:103], v[180:183], v[204:207], v[100:103]
	v_mfma_f32_16x16x32_bf16 v[96:99], v[188:191], v[204:207], v[96:99]
	v_mfma_f32_16x16x32_bf16 v[84:87], v[180:183], v[222:225], v[84:87]
	v_mfma_f32_16x16x32_bf16 v[80:83], v[188:191], v[222:225], v[80:83]
	v_mfma_f32_16x16x32_bf16 v[68:71], v[180:183], v[230:233], v[68:71]
	v_mfma_f32_16x16x32_bf16 v[64:67], v[188:191], v[230:233], v[64:67]
	s_setprio 0
	s_barrier
	s_add_i32 s67, s67, s19
	s_mov_b32 m0, s67
	ds_read_b128 v[192:195], v153 offset:16384
	ds_read_b128 v[196:199], v153 offset:17408
	ds_read_b128 v[200:203], v153 offset:18432
	ds_read_b128 v[204:207], v153 offset:19456
	ds_read_b128 v[218:221], v153 offset:20480
	ds_read_b128 v[222:225], v153 offset:21504
	ds_read_b128 v[226:229], v153 offset:22528
	ds_read_b128 v[230:233], v153 offset:23552
	global_load_lds_dwordx4 v132, s[42:43]
	s_add_i32 m0, s67, 0x2000
	s_add_u32 s68, s42, 0x10000
	s_addc_u32 s69, s43, 0
	s_add_i32 s67, s70, s19
	global_load_lds_dwordx4 v128, s[42:43]
	s_mov_b32 m0, s67
	s_nop 0
	global_load_lds_dwordx4 v132, s[68:69]
	s_add_i32 m0, s67, 0x2000
	s_nop 0
	global_load_lds_dwordx4 v128, s[68:69]
	s_mov_b32 m0, s46
	s_nop 0
	global_load_lds_dwordx4 v134, s[44:45]
	s_mov_b32 m0, s47
	s_nop 0
	global_load_lds_dwordx4 v130, s[44:45]
	s_waitcnt vmcnt(8)
	s_waitcnt lgkmcnt(0)
	s_barrier
	s_setprio 1
	s_waitcnt lgkmcnt(0)
	v_mfma_f32_16x16x32_bf16 v[60:63], v[160:163], v[192:195], 0
	v_mfma_f32_16x16x32_bf16 v[56:59], v[168:171], v[192:195], 0
	v_mfma_f32_16x16x32_bf16 v[44:47], v[160:163], v[200:203], 0
	v_mfma_f32_16x16x32_bf16 v[40:43], v[168:171], v[200:203], 0
	v_mfma_f32_16x16x32_bf16 v[28:31], v[160:163], v[218:221], 0
	v_mfma_f32_16x16x32_bf16 v[24:27], v[168:171], v[218:221], 0
	v_mfma_f32_16x16x32_bf16 v[12:15], v[160:163], v[226:229], 0
	v_mfma_f32_16x16x32_bf16 v[8:11], v[168:171], v[226:229], 0
	v_mfma_f32_16x16x32_bf16 v[60:63], v[164:167], v[196:199], v[60:63]
	v_mfma_f32_16x16x32_bf16 v[56:59], v[172:175], v[196:199], v[56:59]
	v_mfma_f32_16x16x32_bf16 v[44:47], v[164:167], v[204:207], v[44:47]
	v_mfma_f32_16x16x32_bf16 v[40:43], v[172:175], v[204:207], v[40:43]
	v_mfma_f32_16x16x32_bf16 v[28:31], v[164:167], v[222:225], v[28:31]
	v_mfma_f32_16x16x32_bf16 v[24:27], v[172:175], v[222:225], v[24:27]
	v_mfma_f32_16x16x32_bf16 v[12:15], v[164:167], v[230:233], v[12:15]
	v_mfma_f32_16x16x32_bf16 v[8:11], v[172:175], v[230:233], v[8:11]
	s_setprio 0
	s_setprio 1
	v_mfma_f32_16x16x32_bf16 v[52:55], v[176:179], v[192:195], 0
	v_mfma_f32_16x16x32_bf16 v[48:51], v[184:187], v[192:195], 0
	v_mfma_f32_16x16x32_bf16 v[36:39], v[176:179], v[200:203], 0
	v_mfma_f32_16x16x32_bf16 v[32:35], v[184:187], v[200:203], 0
	v_mfma_f32_16x16x32_bf16 v[20:23], v[176:179], v[218:221], 0
	v_mfma_f32_16x16x32_bf16 v[16:19], v[184:187], v[218:221], 0
	v_mfma_f32_16x16x32_bf16 v[4:7], v[176:179], v[226:229], 0
	v_mfma_f32_16x16x32_bf16 v[0:3], v[184:187], v[226:229], 0
	v_mfma_f32_16x16x32_bf16 v[52:55], v[180:183], v[196:199], v[52:55]
	v_mfma_f32_16x16x32_bf16 v[48:51], v[188:191], v[196:199], v[48:51]
	v_mfma_f32_16x16x32_bf16 v[36:39], v[180:183], v[204:207], v[36:39]
	v_mfma_f32_16x16x32_bf16 v[32:35], v[188:191], v[204:207], v[32:35]
	v_mfma_f32_16x16x32_bf16 v[20:23], v[180:183], v[222:225], v[20:23]
	v_mfma_f32_16x16x32_bf16 v[16:19], v[188:191], v[222:225], v[16:19]
	v_mfma_f32_16x16x32_bf16 v[4:7], v[180:183], v[230:233], v[4:7]
	v_mfma_f32_16x16x32_bf16 v[0:3], v[188:191], v[230:233], v[0:3]
	s_setprio 0
	s_barrier
	s_branch .Lwin_mid
.LBB0_163:
	s_add_u32 s42, s38, 0x6000
	s_addc_u32 s43, s39, 0
	s_and_b64 s[40:41], s[40:41], exec
	s_cselect_b32 s44, s60, s42
	s_cselect_b32 s45, s29, s43
	s_cselect_b32 s43, s27, s65
	s_cselect_b32 s42, s61, s64
	s_add_u32 s40, s44, 0x8000
	s_addc_u32 s41, s45, 0
	s_add_i32 s67, 0, 0x10000
	v_add_u32_e32 v159, s67, v143
	s_add_i32 s70, 0, 0x14000
	ds_read_b128 v[160:163], v159
	ds_read_b128 v[164:167], v159 offset:1024
	ds_read_b128 v[168:171], v159 offset:2048
	ds_read_b128 v[172:175], v159 offset:3072
	v_add_u32_e32 v159, s70, v143
	ds_read_b128 v[176:179], v159
	ds_read_b128 v[180:183], v159 offset:1024
	ds_read_b128 v[184:187], v159 offset:2048
	ds_read_b128 v[188:191], v159 offset:3072
	s_add_i32 m0, s46, 0xc000
	ds_read_b128 v[192:195], v153
	ds_read_b128 v[196:199], v153 offset:1024
	ds_read_b128 v[200:203], v153 offset:2048
	ds_read_b128 v[204:207], v153 offset:3072
	ds_read_b128 v[218:221], v153 offset:4096
	ds_read_b128 v[222:225], v153 offset:5120
	ds_read_b128 v[226:229], v153 offset:6144
	ds_read_b128 v[230:233], v153 offset:7168
	global_load_lds_dwordx4 v136, s[38:39]
	s_add_i32 m0, s46, 0xe000
	s_nop 0
	global_load_lds_dwordx4 v138, s[38:39]
	s_waitcnt vmcnt(8)
	s_waitcnt lgkmcnt(0)
	s_barrier
	s_setprio 1
	s_waitcnt lgkmcnt(0)
	v_mfma_f32_16x16x32_bf16 v[124:127], v[160:163], v[192:195], v[124:127]
	v_mfma_f32_16x16x32_bf16 v[120:123], v[168:171], v[192:195], v[120:123]
	v_mfma_f32_16x16x32_bf16 v[108:111], v[160:163], v[200:203], v[108:111]
	v_mfma_f32_16x16x32_bf16 v[104:107], v[168:171], v[200:203], v[104:107]
	v_mfma_f32_16x16x32_bf16 v[92:95], v[160:163], v[218:221], v[92:95]
	v_mfma_f32_16x16x32_bf16 v[88:91], v[168:171], v[218:221], v[88:91]
	v_mfma_f32_16x16x32_bf16 v[76:79], v[160:163], v[226:229], v[76:79]
	v_mfma_f32_16x16x32_bf16 v[72:75], v[168:171], v[226:229], v[72:75]
	v_mfma_f32_16x16x32_bf16 v[124:127], v[164:167], v[196:199], v[124:127]
	v_mfma_f32_16x16x32_bf16 v[120:123], v[172:175], v[196:199], v[120:123]
	v_mfma_f32_16x16x32_bf16 v[108:111], v[164:167], v[204:207], v[108:111]
	v_mfma_f32_16x16x32_bf16 v[104:107], v[172:175], v[204:207], v[104:107]
	v_mfma_f32_16x16x32_bf16 v[92:95], v[164:167], v[222:225], v[92:95]
	v_mfma_f32_16x16x32_bf16 v[88:91], v[172:175], v[222:225], v[88:91]
	v_mfma_f32_16x16x32_bf16 v[76:79], v[164:167], v[230:233], v[76:79]
	v_mfma_f32_16x16x32_bf16 v[72:75], v[172:175], v[230:233], v[72:75]
	s_setprio 0
	s_setprio 1
	v_mfma_f32_16x16x32_bf16 v[116:119], v[176:179], v[192:195], v[116:119]
	v_mfma_f32_16x16x32_bf16 v[112:115], v[184:187], v[192:195], v[112:115]
	v_mfma_f32_16x16x32_bf16 v[100:103], v[176:179], v[200:203], v[100:103]
	v_mfma_f32_16x16x32_bf16 v[96:99], v[184:187], v[200:203], v[96:99]
	v_mfma_f32_16x16x32_bf16 v[84:87], v[176:179], v[218:221], v[84:87]
	v_mfma_f32_16x16x32_bf16 v[80:83], v[184:187], v[218:221], v[80:83]
	v_mfma_f32_16x16x32_bf16 v[68:71], v[176:179], v[226:229], v[68:71]
	v_mfma_f32_16x16x32_bf16 v[64:67], v[184:187], v[226:229], v[64:67]
	v_mfma_f32_16x16x32_bf16 v[116:119], v[180:183], v[196:199], v[116:119]
	v_mfma_f32_16x16x32_bf16 v[112:115], v[188:191], v[196:199], v[112:115]
	v_mfma_f32_16x16x32_bf16 v[100:103], v[180:183], v[204:207], v[100:103]
	v_mfma_f32_16x16x32_bf16 v[96:99], v[188:191], v[204:207], v[96:99]
	v_mfma_f32_16x16x32_bf16 v[84:87], v[180:183], v[222:225], v[84:87]
	v_mfma_f32_16x16x32_bf16 v[80:83], v[188:191], v[222:225], v[80:83]
	v_mfma_f32_16x16x32_bf16 v[68:71], v[180:183], v[230:233], v[68:71]
	v_mfma_f32_16x16x32_bf16 v[64:67], v[188:191], v[230:233], v[64:67]
	s_setprio 0
	s_barrier
	s_add_i32 s67, s67, s19
	s_mov_b32 m0, s67
	ds_read_b128 v[192:195], v153 offset:16384
	ds_read_b128 v[196:199], v153 offset:17408
	ds_read_b128 v[200:203], v153 offset:18432
	ds_read_b128 v[204:207], v153 offset:19456
	ds_read_b128 v[218:221], v153 offset:20480
	ds_read_b128 v[222:225], v153 offset:21504
	ds_read_b128 v[226:229], v153 offset:22528
	ds_read_b128 v[230:233], v153 offset:23552
	global_load_lds_dwordx4 v132, s[42:43]
	s_add_i32 m0, s67, 0x2000
	s_add_u32 s68, s42, 0x10000
	s_addc_u32 s69, s43, 0
	s_add_i32 s67, s70, s19
	global_load_lds_dwordx4 v128, s[42:43]
	s_mov_b32 m0, s67
	s_nop 0
	global_load_lds_dwordx4 v132, s[68:69]
	s_add_i32 m0, s67, 0x2000
	s_nop 0
	global_load_lds_dwordx4 v128, s[68:69]
	s_mov_b32 m0, s46
	s_nop 0
	global_load_lds_dwordx4 v134, s[44:45]
	s_mov_b32 m0, s47
	s_nop 0
	global_load_lds_dwordx4 v130, s[44:45]
	s_waitcnt vmcnt(8)
	s_waitcnt lgkmcnt(0)
	s_barrier
	s_setprio 1
	s_waitcnt lgkmcnt(0)
	v_mfma_f32_16x16x32_bf16 v[60:63], v[160:163], v[192:195], v[60:63]
	v_mfma_f32_16x16x32_bf16 v[56:59], v[168:171], v[192:195], v[56:59]
	v_mfma_f32_16x16x32_bf16 v[44:47], v[160:163], v[200:203], v[44:47]
	v_mfma_f32_16x16x32_bf16 v[40:43], v[168:171], v[200:203], v[40:43]
	v_mfma_f32_16x16x32_bf16 v[28:31], v[160:163], v[218:221], v[28:31]
	v_mfma_f32_16x16x32_bf16 v[24:27], v[168:171], v[218:221], v[24:27]
	v_mfma_f32_16x16x32_bf16 v[12:15], v[160:163], v[226:229], v[12:15]
	v_mfma_f32_16x16x32_bf16 v[8:11], v[168:171], v[226:229], v[8:11]
	v_mfma_f32_16x16x32_bf16 v[60:63], v[164:167], v[196:199], v[60:63]
	v_mfma_f32_16x16x32_bf16 v[56:59], v[172:175], v[196:199], v[56:59]
	v_mfma_f32_16x16x32_bf16 v[44:47], v[164:167], v[204:207], v[44:47]
	v_mfma_f32_16x16x32_bf16 v[40:43], v[172:175], v[204:207], v[40:43]
	v_mfma_f32_16x16x32_bf16 v[28:31], v[164:167], v[222:225], v[28:31]
	v_mfma_f32_16x16x32_bf16 v[24:27], v[172:175], v[222:225], v[24:27]
	v_mfma_f32_16x16x32_bf16 v[12:15], v[164:167], v[230:233], v[12:15]
	v_mfma_f32_16x16x32_bf16 v[8:11], v[172:175], v[230:233], v[8:11]
	s_setprio 0
	s_setprio 1
	v_mfma_f32_16x16x32_bf16 v[52:55], v[176:179], v[192:195], v[52:55]
	v_mfma_f32_16x16x32_bf16 v[48:51], v[184:187], v[192:195], v[48:51]
	v_mfma_f32_16x16x32_bf16 v[36:39], v[176:179], v[200:203], v[36:39]
	v_mfma_f32_16x16x32_bf16 v[32:35], v[184:187], v[200:203], v[32:35]
	v_mfma_f32_16x16x32_bf16 v[20:23], v[176:179], v[218:221], v[20:23]
	v_mfma_f32_16x16x32_bf16 v[16:19], v[184:187], v[218:221], v[16:19]
	v_mfma_f32_16x16x32_bf16 v[4:7], v[176:179], v[226:229], v[4:7]
	v_mfma_f32_16x16x32_bf16 v[0:3], v[184:187], v[226:229], v[0:3]
	v_mfma_f32_16x16x32_bf16 v[52:55], v[180:183], v[196:199], v[52:55]
	v_mfma_f32_16x16x32_bf16 v[48:51], v[188:191], v[196:199], v[48:51]
	v_mfma_f32_16x16x32_bf16 v[36:39], v[180:183], v[204:207], v[36:39]
	v_mfma_f32_16x16x32_bf16 v[32:35], v[188:191], v[204:207], v[32:35]
	v_mfma_f32_16x16x32_bf16 v[20:23], v[180:183], v[222:225], v[20:23]
	v_mfma_f32_16x16x32_bf16 v[16:19], v[188:191], v[222:225], v[16:19]
	v_mfma_f32_16x16x32_bf16 v[4:7], v[180:183], v[230:233], v[4:7]
	v_mfma_f32_16x16x32_bf16 v[0:3], v[188:191], v[230:233], v[0:3]
	s_setprio 0
	s_barrier
.Lwin_mid:
	s_add_i32 s67, 0, 0x18000
	v_add_u32_e32 v159, s67, v143
	s_add_i32 s68, 0, 0x1c000
	ds_read_b128 v[160:163], v159
	ds_read_b128 v[164:167], v159 offset:1024
	ds_read_b128 v[168:171], v159 offset:2048
	ds_read_b128 v[172:175], v159 offset:3072
	v_add_u32_e32 v159, s68, v143
	ds_read_b128 v[176:179], v159
	ds_read_b128 v[180:183], v159 offset:1024
	ds_read_b128 v[184:187], v159 offset:2048
	ds_read_b128 v[188:191], v159 offset:3072
	s_add_u32 s44, s44, 0x2000
	s_addc_u32 s45, s45, 0
	s_mov_b32 m0, s48
	ds_read_b128 v[192:195], v153 offset:32768
	ds_read_b128 v[196:199], v153 offset:33792
	ds_read_b128 v[200:203], v153 offset:34816
	ds_read_b128 v[204:207], v153 offset:35840
	ds_read_b128 v[218:221], v153 offset:36864
	ds_read_b128 v[222:225], v153 offset:37888
	ds_read_b128 v[226:229], v153 offset:38912
	ds_read_b128 v[230:233], v153 offset:39936
	global_load_lds_dwordx4 v134, s[44:45]
	s_mov_b32 m0, s49
	s_nop 0
	global_load_lds_dwordx4 v130, s[44:45]
	s_waitcnt vmcnt(8)
	s_waitcnt lgkmcnt(0)
	s_barrier
	s_setprio 1
	s_waitcnt lgkmcnt(0)
	v_mfma_f32_16x16x32_bf16 v[124:127], v[160:163], v[192:195], v[124:127]
	v_mfma_f32_16x16x32_bf16 v[120:123], v[168:171], v[192:195], v[120:123]
	v_mfma_f32_16x16x32_bf16 v[108:111], v[160:163], v[200:203], v[108:111]
	v_mfma_f32_16x16x32_bf16 v[104:107], v[168:171], v[200:203], v[104:107]
	v_mfma_f32_16x16x32_bf16 v[92:95], v[160:163], v[218:221], v[92:95]
	v_mfma_f32_16x16x32_bf16 v[88:91], v[168:171], v[218:221], v[88:91]
	v_mfma_f32_16x16x32_bf16 v[76:79], v[160:163], v[226:229], v[76:79]
	v_mfma_f32_16x16x32_bf16 v[72:75], v[168:171], v[226:229], v[72:75]
	v_mfma_f32_16x16x32_bf16 v[124:127], v[164:167], v[196:199], v[124:127]
	v_mfma_f32_16x16x32_bf16 v[120:123], v[172:175], v[196:199], v[120:123]
	v_mfma_f32_16x16x32_bf16 v[108:111], v[164:167], v[204:207], v[108:111]
	v_mfma_f32_16x16x32_bf16 v[104:107], v[172:175], v[204:207], v[104:107]
	v_mfma_f32_16x16x32_bf16 v[92:95], v[164:167], v[222:225], v[92:95]
	v_mfma_f32_16x16x32_bf16 v[88:91], v[172:175], v[222:225], v[88:91]
	v_mfma_f32_16x16x32_bf16 v[76:79], v[164:167], v[230:233], v[76:79]
	v_mfma_f32_16x16x32_bf16 v[72:75], v[172:175], v[230:233], v[72:75]
	s_setprio 0
	s_setprio 1
	v_mfma_f32_16x16x32_bf16 v[116:119], v[176:179], v[192:195], v[116:119]
	v_mfma_f32_16x16x32_bf16 v[112:115], v[184:187], v[192:195], v[112:115]
	v_mfma_f32_16x16x32_bf16 v[100:103], v[176:179], v[200:203], v[100:103]
	v_mfma_f32_16x16x32_bf16 v[96:99], v[184:187], v[200:203], v[96:99]
	v_mfma_f32_16x16x32_bf16 v[84:87], v[176:179], v[218:221], v[84:87]
	v_mfma_f32_16x16x32_bf16 v[80:83], v[184:187], v[218:221], v[80:83]
	v_mfma_f32_16x16x32_bf16 v[68:71], v[176:179], v[226:229], v[68:71]
	v_mfma_f32_16x16x32_bf16 v[64:67], v[184:187], v[226:229], v[64:67]
	v_mfma_f32_16x16x32_bf16 v[116:119], v[180:183], v[196:199], v[116:119]
	v_mfma_f32_16x16x32_bf16 v[112:115], v[188:191], v[196:199], v[112:115]
	v_mfma_f32_16x16x32_bf16 v[100:103], v[180:183], v[204:207], v[100:103]
	v_mfma_f32_16x16x32_bf16 v[96:99], v[188:191], v[204:207], v[96:99]
	v_mfma_f32_16x16x32_bf16 v[84:87], v[180:183], v[222:225], v[84:87]
	v_mfma_f32_16x16x32_bf16 v[80:83], v[188:191], v[222:225], v[80:83]
	v_mfma_f32_16x16x32_bf16 v[68:71], v[180:183], v[230:233], v[68:71]
	v_mfma_f32_16x16x32_bf16 v[64:67], v[188:191], v[230:233], v[64:67]
	s_setprio 0
	s_barrier
	s_add_i32 s44, s67, s19
	s_add_u32 s98, s42, 0x80
	s_addc_u32 s99, s43, 0
	s_mov_b32 m0, s44
	ds_read_b128 v[192:195], v153 offset:49152
	ds_read_b128 v[196:199], v153 offset:50176
	ds_read_b128 v[200:203], v153 offset:51200
	ds_read_b128 v[204:207], v153 offset:52224
	ds_read_b128 v[218:221], v153 offset:53248
	ds_read_b128 v[222:225], v153 offset:54272
	ds_read_b128 v[226:229], v153 offset:55296
	ds_read_b128 v[230:233], v153 offset:56320
	global_load_lds_dwordx4 v132, s[98:99]
	s_add_i32 m0, s44, 0x2000
	s_add_u32 s42, s42, 0x10080
	s_addc_u32 s43, s43, 0
	s_add_i32 s44, s68, s19
	global_load_lds_dwordx4 v128, s[98:99]
	s_mov_b32 m0, s44
	s_nop 0
	global_load_lds_dwordx4 v132, s[42:43]
	s_add_i32 m0, s44, 0x2000
	s_nop 0
	global_load_lds_dwordx4 v128, s[42:43]
	s_mov_b32 m0, s52
	s_nop 0
	global_load_lds_dwordx4 v134, s[40:41]
	s_mov_b32 m0, s53
	s_nop 0
	global_load_lds_dwordx4 v130, s[40:41]
	s_waitcnt vmcnt(8)
	s_waitcnt lgkmcnt(0)
	s_barrier
	s_setprio 1
	s_waitcnt lgkmcnt(0)
	v_mfma_f32_16x16x32_bf16 v[60:63], v[160:163], v[192:195], v[60:63]
	v_mfma_f32_16x16x32_bf16 v[56:59], v[168:171], v[192:195], v[56:59]
	v_mfma_f32_16x16x32_bf16 v[44:47], v[160:163], v[200:203], v[44:47]
	v_mfma_f32_16x16x32_bf16 v[40:43], v[168:171], v[200:203], v[40:43]
	v_mfma_f32_16x16x32_bf16 v[28:31], v[160:163], v[218:221], v[28:31]
	v_mfma_f32_16x16x32_bf16 v[24:27], v[168:171], v[218:221], v[24:27]
	v_mfma_f32_16x16x32_bf16 v[12:15], v[160:163], v[226:229], v[12:15]
	v_mfma_f32_16x16x32_bf16 v[8:11], v[168:171], v[226:229], v[8:11]
	v_mfma_f32_16x16x32_bf16 v[60:63], v[164:167], v[196:199], v[60:63]
	v_mfma_f32_16x16x32_bf16 v[56:59], v[172:175], v[196:199], v[56:59]
	v_mfma_f32_16x16x32_bf16 v[44:47], v[164:167], v[204:207], v[44:47]
	v_mfma_f32_16x16x32_bf16 v[40:43], v[172:175], v[204:207], v[40:43]
	v_mfma_f32_16x16x32_bf16 v[28:31], v[164:167], v[222:225], v[28:31]
	v_mfma_f32_16x16x32_bf16 v[24:27], v[172:175], v[222:225], v[24:27]
	v_mfma_f32_16x16x32_bf16 v[12:15], v[164:167], v[230:233], v[12:15]
	v_mfma_f32_16x16x32_bf16 v[8:11], v[172:175], v[230:233], v[8:11]
	s_setprio 0
	s_setprio 1
	v_mfma_f32_16x16x32_bf16 v[52:55], v[176:179], v[192:195], v[52:55]
	v_mfma_f32_16x16x32_bf16 v[48:51], v[184:187], v[192:195], v[48:51]
	v_mfma_f32_16x16x32_bf16 v[36:39], v[176:179], v[200:203], v[36:39]
	v_mfma_f32_16x16x32_bf16 v[32:35], v[184:187], v[200:203], v[32:35]
	v_mfma_f32_16x16x32_bf16 v[20:23], v[176:179], v[218:221], v[20:23]
	v_mfma_f32_16x16x32_bf16 v[16:19], v[184:187], v[218:221], v[16:19]
	v_mfma_f32_16x16x32_bf16 v[4:7], v[176:179], v[226:229], v[4:7]
	v_mfma_f32_16x16x32_bf16 v[0:3], v[184:187], v[226:229], v[0:3]
	v_mfma_f32_16x16x32_bf16 v[52:55], v[180:183], v[196:199], v[52:55]
	v_mfma_f32_16x16x32_bf16 v[48:51], v[188:191], v[196:199], v[48:51]
	v_mfma_f32_16x16x32_bf16 v[36:39], v[180:183], v[204:207], v[36:39]
	v_mfma_f32_16x16x32_bf16 v[32:35], v[188:191], v[204:207], v[32:35]
	v_mfma_f32_16x16x32_bf16 v[20:23], v[180:183], v[222:225], v[20:23]
	v_mfma_f32_16x16x32_bf16 v[16:19], v[188:191], v[222:225], v[16:19]
	v_mfma_f32_16x16x32_bf16 v[4:7], v[180:183], v[230:233], v[4:7]
	v_mfma_f32_16x16x32_bf16 v[0:3], v[188:191], v[230:233], v[0:3]
	s_setprio 0
	s_barrier
	s_add_i32 s66, s66, 2
	s_add_u32 s64, s64, 0x100
	s_addc_u32 s65, s65, 0
	s_add_u32 s38, s38, 0x10000
	s_addc_u32 s39, s39, 0
	s_cmp_gt_u32 s66, 13
	s_cbranch_scc1 .LBB0_166

.LBB0_433:
	s_ashr_i32 s61, s60, 31
	s_lshl_b64 s[2:3], s[60:61], 19
	s_add_u32 s70, s50, s2
	s_addc_u32 s71, s51, s3
	s_and_b64 s[2:3], s[36:37], exec
	s_cselect_b32 s2, s71, s35
	s_cselect_b32 s3, s70, s34
	s_ashr_i32 s57, s56, 31
	s_lshl_b64 s[40:41], s[56:57], 19
	s_add_u32 s76, s18, s40
	s_addc_u32 s77, s19, s41
	s_and_b64 s[40:41], s[36:37], exec
	s_cselect_b32 s23, s77, s79
	s_cselect_b32 s29, s76, s78
	s_add_u32 s34, s34, 0x40080
	s_addc_u32 s35, s35, 0
	s_add_u32 s42, s78, 0x100
	v_mov_b32_e32 v0, 0
	s_addc_u32 s43, s79, 0
	s_mov_b32 s44, -2
	s_add_u32 s38, s34, 0xfffc0080
	s_addc_u32 s39, s35, -1
	s_add_i32 s45, 0, 0x10000
	s_cmp_eq_u32 s44, 12
	s_cselect_b32 s41, s2, s39
	s_cselect_b32 s40, s3, s38
	s_cselect_b32 s39, s23, s43
	s_cselect_b32 s38, s29, s42
	s_add_i32 s57, 0, 0x14000
	v_add_u32_e32 v132, s45, v238
	v_add_u32_e32 v148, s57, v238
	ds_read_b128 v[112:115], v132
	ds_read_b128 v[116:119], v132 offset:1024
	ds_read_b128 v[120:123], v132 offset:2048
	ds_read_b128 v[132:135], v132 offset:3072
	ds_read_b128 v[136:139], v148
	ds_read_b128 v[140:143], v148 offset:1024
	ds_read_b128 v[144:147], v148 offset:2048
	ds_read_b128 v[148:151], v148 offset:3072
	s_add_i32 m0, s33, 0xc000
	ds_read_b128 v[152:155], v239
	ds_read_b128 v[156:159], v239 offset:1024
	ds_read_b128 v[168:171], v239 offset:2048
	ds_read_b128 v[172:175], v239 offset:3072
	ds_read_b128 v[176:179], v239 offset:4096
	ds_read_b128 v[180:183], v239 offset:5120
	ds_read_b128 v[184:187], v239 offset:6144
	ds_read_b128 v[188:191], v239 offset:7168
	global_load_lds_dwordx4 v224, s[34:35]
	s_add_i32 m0, s33, 0xe000
	s_nop 0
	global_load_lds_dwordx4 v226, s[34:35]
	s_waitcnt vmcnt(8)
	s_waitcnt lgkmcnt(0)
	s_barrier
	s_setprio 1
	s_waitcnt lgkmcnt(0)
	v_mfma_f32_16x16x32_bf16 v[164:167], v[112:115], v[152:155], 0
	v_mfma_f32_16x16x32_bf16 v[160:163], v[120:123], v[152:155], 0
	v_mfma_f32_16x16x32_bf16 v[108:111], v[112:115], v[168:171], 0
	v_mfma_f32_16x16x32_bf16 v[104:107], v[120:123], v[168:171], 0
	v_mfma_f32_16x16x32_bf16 v[92:95], v[112:115], v[176:179], 0
	v_mfma_f32_16x16x32_bf16 v[88:91], v[120:123], v[176:179], 0
	v_mfma_f32_16x16x32_bf16 v[76:79], v[112:115], v[184:187], 0
	v_mfma_f32_16x16x32_bf16 v[72:75], v[120:123], v[184:187], 0
	v_mfma_f32_16x16x32_bf16 v[164:167], v[116:119], v[156:159], v[164:167]
	v_mfma_f32_16x16x32_bf16 v[160:163], v[132:135], v[156:159], v[160:163]
	v_mfma_f32_16x16x32_bf16 v[108:111], v[116:119], v[172:175], v[108:111]
	v_mfma_f32_16x16x32_bf16 v[104:107], v[132:135], v[172:175], v[104:107]
	v_mfma_f32_16x16x32_bf16 v[92:95], v[116:119], v[180:183], v[92:95]
	v_mfma_f32_16x16x32_bf16 v[88:91], v[132:135], v[180:183], v[88:91]
	v_mfma_f32_16x16x32_bf16 v[76:79], v[116:119], v[188:191], v[76:79]
	v_mfma_f32_16x16x32_bf16 v[72:75], v[132:135], v[188:191], v[72:75]
	s_setprio 0
	s_setprio 1
	v_mfma_f32_16x16x32_bf16 v[128:131], v[136:139], v[152:155], 0
	v_mfma_f32_16x16x32_bf16 v[124:127], v[144:147], v[152:155], 0
	v_mfma_f32_16x16x32_bf16 v[100:103], v[136:139], v[168:171], 0
	v_mfma_f32_16x16x32_bf16 v[96:99], v[144:147], v[168:171], 0
	v_mfma_f32_16x16x32_bf16 v[84:87], v[136:139], v[176:179], 0
	v_mfma_f32_16x16x32_bf16 v[80:83], v[144:147], v[176:179], 0
	v_mfma_f32_16x16x32_bf16 v[68:71], v[136:139], v[184:187], 0
	v_mfma_f32_16x16x32_bf16 v[64:67], v[144:147], v[184:187], 0
	v_mfma_f32_16x16x32_bf16 v[128:131], v[140:143], v[156:159], v[128:131]
	v_mfma_f32_16x16x32_bf16 v[124:127], v[148:151], v[156:159], v[124:127]
	v_mfma_f32_16x16x32_bf16 v[100:103], v[140:143], v[172:175], v[100:103]
	v_mfma_f32_16x16x32_bf16 v[96:99], v[148:151], v[172:175], v[96:99]
	v_mfma_f32_16x16x32_bf16 v[84:87], v[140:143], v[180:183], v[84:87]
	v_mfma_f32_16x16x32_bf16 v[80:83], v[148:151], v[180:183], v[80:83]
	v_mfma_f32_16x16x32_bf16 v[68:71], v[140:143], v[188:191], v[68:71]
	v_mfma_f32_16x16x32_bf16 v[64:67], v[148:151], v[188:191], v[64:67]
	s_setprio 0
	s_barrier
	s_add_i32 s45, s45, s64
	s_mov_b32 m0, s45
	ds_read_b128 v[152:155], v239 offset:16384
	ds_read_b128 v[156:159], v239 offset:17408
	ds_read_b128 v[168:171], v239 offset:18432
	ds_read_b128 v[172:175], v239 offset:19456
	ds_read_b128 v[176:179], v239 offset:20480
	ds_read_b128 v[180:183], v239 offset:21504
	ds_read_b128 v[184:187], v239 offset:22528
	ds_read_b128 v[188:191], v239 offset:23552
	global_load_lds_dwordx4 v208, s[38:39]
	s_add_i32 m0, s45, 0x2000
	s_add_u32 s48, s38, 0x40000
	s_addc_u32 s49, s39, 0
	s_add_i32 s45, s57, s64
	global_load_lds_dwordx4 v222, s[38:39]
	s_mov_b32 m0, s45
	s_nop 0
	global_load_lds_dwordx4 v208, s[48:49]
	s_add_i32 m0, s45, 0x2000
	s_nop 0
	global_load_lds_dwordx4 v222, s[48:49]
	s_add_u32 s100, s40, 0x80
	s_addc_u32 s101, s41, 0
	s_mov_b32 m0, s33
	s_nop 0
	global_load_lds_dwordx4 v218, s[40:41]
	s_mov_b32 m0, s11
	s_nop 0
	global_load_lds_dwordx4 v220, s[40:41]
	s_waitcnt vmcnt(8)
	s_waitcnt lgkmcnt(0)
	s_barrier
	s_setprio 1
	s_waitcnt lgkmcnt(0)
	v_mfma_f32_16x16x32_bf16 v[60:63], v[112:115], v[152:155], 0
	v_mfma_f32_16x16x32_bf16 v[56:59], v[120:123], v[152:155], 0
	v_mfma_f32_16x16x32_bf16 v[44:47], v[112:115], v[168:171], 0
	v_mfma_f32_16x16x32_bf16 v[40:43], v[120:123], v[168:171], 0
	v_mfma_f32_16x16x32_bf16 v[28:31], v[112:115], v[176:179], 0
	v_mfma_f32_16x16x32_bf16 v[24:27], v[120:123], v[176:179], 0
	v_mfma_f32_16x16x32_bf16 v[12:15], v[112:115], v[184:187], 0
	v_mfma_f32_16x16x32_bf16 v[8:11], v[120:123], v[184:187], 0
	v_mfma_f32_16x16x32_bf16 v[60:63], v[116:119], v[156:159], v[60:63]
	v_mfma_f32_16x16x32_bf16 v[56:59], v[132:135], v[156:159], v[56:59]
	v_mfma_f32_16x16x32_bf16 v[44:47], v[116:119], v[172:175], v[44:47]
	v_mfma_f32_16x16x32_bf16 v[40:43], v[132:135], v[172:175], v[40:43]
	v_mfma_f32_16x16x32_bf16 v[28:31], v[116:119], v[180:183], v[28:31]
	v_mfma_f32_16x16x32_bf16 v[24:27], v[132:135], v[180:183], v[24:27]
	v_mfma_f32_16x16x32_bf16 v[12:15], v[116:119], v[188:191], v[12:15]
	v_mfma_f32_16x16x32_bf16 v[8:11], v[132:135], v[188:191], v[8:11]
	s_setprio 0
	s_setprio 1
	v_mfma_f32_16x16x32_bf16 v[52:55], v[136:139], v[152:155], 0
	v_mfma_f32_16x16x32_bf16 v[48:51], v[144:147], v[152:155], 0
	v_mfma_f32_16x16x32_bf16 v[36:39], v[136:139], v[168:171], 0
	v_mfma_f32_16x16x32_bf16 v[32:35], v[144:147], v[168:171], 0
	v_mfma_f32_16x16x32_bf16 v[20:23], v[136:139], v[176:179], 0
	v_mfma_f32_16x16x32_bf16 v[16:19], v[144:147], v[176:179], 0
	v_mfma_f32_16x16x32_bf16 v[4:7], v[136:139], v[184:187], 0
	v_mfma_f32_16x16x32_bf16 v[0:3], v[144:147], v[184:187], 0
	v_mfma_f32_16x16x32_bf16 v[52:55], v[140:143], v[156:159], v[52:55]
	v_mfma_f32_16x16x32_bf16 v[48:51], v[148:151], v[156:159], v[48:51]
	v_mfma_f32_16x16x32_bf16 v[36:39], v[140:143], v[172:175], v[36:39]
	v_mfma_f32_16x16x32_bf16 v[32:35], v[148:151], v[172:175], v[32:35]
	v_mfma_f32_16x16x32_bf16 v[20:23], v[140:143], v[180:183], v[20:23]
	v_mfma_f32_16x16x32_bf16 v[16:19], v[148:151], v[180:183], v[16:19]
	v_mfma_f32_16x16x32_bf16 v[4:7], v[140:143], v[188:191], v[4:7]
	v_mfma_f32_16x16x32_bf16 v[0:3], v[148:151], v[188:191], v[0:3]
	s_setprio 0
	s_barrier
	s_branch .Lwout_mid
.LBB0_434:
	s_add_u32 s38, s34, 0xfffc0080
	s_addc_u32 s39, s35, -1
	s_add_i32 s45, 0, 0x10000
	s_cmp_eq_u32 s44, 12
	s_cselect_b32 s41, s2, s39
	s_cselect_b32 s40, s3, s38
	s_cselect_b32 s39, s23, s43
	s_cselect_b32 s38, s29, s42
	s_add_i32 s57, 0, 0x14000
	v_add_u32_e32 v132, s45, v238
	v_add_u32_e32 v148, s57, v238
	ds_read_b128 v[112:115], v132
	ds_read_b128 v[116:119], v132 offset:1024
	ds_read_b128 v[120:123], v132 offset:2048
	ds_read_b128 v[132:135], v132 offset:3072
	ds_read_b128 v[136:139], v148
	ds_read_b128 v[140:143], v148 offset:1024
	ds_read_b128 v[144:147], v148 offset:2048
	ds_read_b128 v[148:151], v148 offset:3072
	s_add_i32 m0, s33, 0xc000
	ds_read_b128 v[152:155], v239
	ds_read_b128 v[156:159], v239 offset:1024
	ds_read_b128 v[168:171], v239 offset:2048
	ds_read_b128 v[172:175], v239 offset:3072
	ds_read_b128 v[176:179], v239 offset:4096
	ds_read_b128 v[180:183], v239 offset:5120
	ds_read_b128 v[184:187], v239 offset:6144
	ds_read_b128 v[188:191], v239 offset:7168
	global_load_lds_dwordx4 v224, s[34:35]
	s_add_i32 m0, s33, 0xe000
	s_nop 0
	global_load_lds_dwordx4 v226, s[34:35]
	s_waitcnt vmcnt(8)
	s_waitcnt lgkmcnt(0)
	s_barrier
	s_setprio 1
	s_waitcnt lgkmcnt(0)
	v_mfma_f32_16x16x32_bf16 v[164:167], v[112:115], v[152:155], v[164:167]
	v_mfma_f32_16x16x32_bf16 v[160:163], v[120:123], v[152:155], v[160:163]
	v_mfma_f32_16x16x32_bf16 v[108:111], v[112:115], v[168:171], v[108:111]
	v_mfma_f32_16x16x32_bf16 v[104:107], v[120:123], v[168:171], v[104:107]
	v_mfma_f32_16x16x32_bf16 v[92:95], v[112:115], v[176:179], v[92:95]
	v_mfma_f32_16x16x32_bf16 v[88:91], v[120:123], v[176:179], v[88:91]
	v_mfma_f32_16x16x32_bf16 v[76:79], v[112:115], v[184:187], v[76:79]
	v_mfma_f32_16x16x32_bf16 v[72:75], v[120:123], v[184:187], v[72:75]
	v_mfma_f32_16x16x32_bf16 v[164:167], v[116:119], v[156:159], v[164:167]
	v_mfma_f32_16x16x32_bf16 v[160:163], v[132:135], v[156:159], v[160:163]
	v_mfma_f32_16x16x32_bf16 v[108:111], v[116:119], v[172:175], v[108:111]
	v_mfma_f32_16x16x32_bf16 v[104:107], v[132:135], v[172:175], v[104:107]
	v_mfma_f32_16x16x32_bf16 v[92:95], v[116:119], v[180:183], v[92:95]
	v_mfma_f32_16x16x32_bf16 v[88:91], v[132:135], v[180:183], v[88:91]
	v_mfma_f32_16x16x32_bf16 v[76:79], v[116:119], v[188:191], v[76:79]
	v_mfma_f32_16x16x32_bf16 v[72:75], v[132:135], v[188:191], v[72:75]
	s_setprio 0
	s_setprio 1
	v_mfma_f32_16x16x32_bf16 v[128:131], v[136:139], v[152:155], v[128:131]
	v_mfma_f32_16x16x32_bf16 v[124:127], v[144:147], v[152:155], v[124:127]
	v_mfma_f32_16x16x32_bf16 v[100:103], v[136:139], v[168:171], v[100:103]
	v_mfma_f32_16x16x32_bf16 v[96:99], v[144:147], v[168:171], v[96:99]
	v_mfma_f32_16x16x32_bf16 v[84:87], v[136:139], v[176:179], v[84:87]
	v_mfma_f32_16x16x32_bf16 v[80:83], v[144:147], v[176:179], v[80:83]
	v_mfma_f32_16x16x32_bf16 v[68:71], v[136:139], v[184:187], v[68:71]
	v_mfma_f32_16x16x32_bf16 v[64:67], v[144:147], v[184:187], v[64:67]
	v_mfma_f32_16x16x32_bf16 v[128:131], v[140:143], v[156:159], v[128:131]
	v_mfma_f32_16x16x32_bf16 v[124:127], v[148:151], v[156:159], v[124:127]
	v_mfma_f32_16x16x32_bf16 v[100:103], v[140:143], v[172:175], v[100:103]
	v_mfma_f32_16x16x32_bf16 v[96:99], v[148:151], v[172:175], v[96:99]
	v_mfma_f32_16x16x32_bf16 v[84:87], v[140:143], v[180:183], v[84:87]
	v_mfma_f32_16x16x32_bf16 v[80:83], v[148:151], v[180:183], v[80:83]
	v_mfma_f32_16x16x32_bf16 v[68:71], v[140:143], v[188:191], v[68:71]
	v_mfma_f32_16x16x32_bf16 v[64:67], v[148:151], v[188:191], v[64:67]
	s_setprio 0
	s_barrier
	s_add_i32 s45, s45, s64
	s_mov_b32 m0, s45
	ds_read_b128 v[152:155], v239 offset:16384
	ds_read_b128 v[156:159], v239 offset:17408
	ds_read_b128 v[168:171], v239 offset:18432
	ds_read_b128 v[172:175], v239 offset:19456
	ds_read_b128 v[176:179], v239 offset:20480
	ds_read_b128 v[180:183], v239 offset:21504
	ds_read_b128 v[184:187], v239 offset:22528
	ds_read_b128 v[188:191], v239 offset:23552
	global_load_lds_dwordx4 v208, s[38:39]
	s_add_i32 m0, s45, 0x2000
	s_add_u32 s48, s38, 0x40000
	s_addc_u32 s49, s39, 0
	s_add_i32 s45, s57, s64
	global_load_lds_dwordx4 v222, s[38:39]
	s_mov_b32 m0, s45
	s_nop 0
	global_load_lds_dwordx4 v208, s[48:49]
	s_add_i32 m0, s45, 0x2000
	s_nop 0
	global_load_lds_dwordx4 v222, s[48:49]
	s_add_u32 s100, s40, 0x80
	s_addc_u32 s101, s41, 0
	s_mov_b32 m0, s33
	s_nop 0
	global_load_lds_dwordx4 v218, s[40:41]
	s_mov_b32 m0, s11
	s_nop 0
	global_load_lds_dwordx4 v220, s[40:41]
	s_waitcnt vmcnt(8)
	s_waitcnt lgkmcnt(0)
	s_barrier
	s_setprio 1
	s_waitcnt lgkmcnt(0)
	v_mfma_f32_16x16x32_bf16 v[60:63], v[112:115], v[152:155], v[60:63]
	v_mfma_f32_16x16x32_bf16 v[56:59], v[120:123], v[152:155], v[56:59]
	v_mfma_f32_16x16x32_bf16 v[44:47], v[112:115], v[168:171], v[44:47]
	v_mfma_f32_16x16x32_bf16 v[40:43], v[120:123], v[168:171], v[40:43]
	v_mfma_f32_16x16x32_bf16 v[28:31], v[112:115], v[176:179], v[28:31]
	v_mfma_f32_16x16x32_bf16 v[24:27], v[120:123], v[176:179], v[24:27]
	v_mfma_f32_16x16x32_bf16 v[12:15], v[112:115], v[184:187], v[12:15]
	v_mfma_f32_16x16x32_bf16 v[8:11], v[120:123], v[184:187], v[8:11]
	v_mfma_f32_16x16x32_bf16 v[60:63], v[116:119], v[156:159], v[60:63]
	v_mfma_f32_16x16x32_bf16 v[56:59], v[132:135], v[156:159], v[56:59]
	v_mfma_f32_16x16x32_bf16 v[44:47], v[116:119], v[172:175], v[44:47]
	v_mfma_f32_16x16x32_bf16 v[40:43], v[132:135], v[172:175], v[40:43]
	v_mfma_f32_16x16x32_bf16 v[28:31], v[116:119], v[180:183], v[28:31]
	v_mfma_f32_16x16x32_bf16 v[24:27], v[132:135], v[180:183], v[24:27]
	v_mfma_f32_16x16x32_bf16 v[12:15], v[116:119], v[188:191], v[12:15]
	v_mfma_f32_16x16x32_bf16 v[8:11], v[132:135], v[188:191], v[8:11]
	s_setprio 0
	s_setprio 1
	v_mfma_f32_16x16x32_bf16 v[52:55], v[136:139], v[152:155], v[52:55]
	v_mfma_f32_16x16x32_bf16 v[48:51], v[144:147], v[152:155], v[48:51]
	v_mfma_f32_16x16x32_bf16 v[36:39], v[136:139], v[168:171], v[36:39]
	v_mfma_f32_16x16x32_bf16 v[32:35], v[144:147], v[168:171], v[32:35]
	v_mfma_f32_16x16x32_bf16 v[20:23], v[136:139], v[176:179], v[20:23]
	v_mfma_f32_16x16x32_bf16 v[16:19], v[144:147], v[176:179], v[16:19]
	v_mfma_f32_16x16x32_bf16 v[4:7], v[136:139], v[184:187], v[4:7]
	v_mfma_f32_16x16x32_bf16 v[0:3], v[144:147], v[184:187], v[0:3]
	v_mfma_f32_16x16x32_bf16 v[52:55], v[140:143], v[156:159], v[52:55]
	v_mfma_f32_16x16x32_bf16 v[48:51], v[148:151], v[156:159], v[48:51]
	v_mfma_f32_16x16x32_bf16 v[36:39], v[140:143], v[172:175], v[36:39]
	v_mfma_f32_16x16x32_bf16 v[32:35], v[148:151], v[172:175], v[32:35]
	v_mfma_f32_16x16x32_bf16 v[20:23], v[140:143], v[180:183], v[20:23]
	v_mfma_f32_16x16x32_bf16 v[16:19], v[148:151], v[180:183], v[16:19]
	v_mfma_f32_16x16x32_bf16 v[4:7], v[140:143], v[188:191], v[4:7]
	v_mfma_f32_16x16x32_bf16 v[0:3], v[148:151], v[188:191], v[0:3]
	s_setprio 0
	s_barrier
.Lwout_mid:
	s_add_i32 s45, 0, 0x18000
	s_add_i32 s48, 0, 0x1c000
	v_add_u32_e32 v132, s45, v238
	v_add_u32_e32 v148, s48, v238
	ds_read_b128 v[112:115], v132
	ds_read_b128 v[116:119], v132 offset:1024
	ds_read_b128 v[120:123], v132 offset:2048
	ds_read_b128 v[132:135], v132 offset:3072
	ds_read_b128 v[136:139], v148
	ds_read_b128 v[140:143], v148 offset:1024
	ds_read_b128 v[144:147], v148 offset:2048
	ds_read_b128 v[148:151], v148 offset:3072
	s_add_u32 s40, s40, 0x40000
	s_addc_u32 s41, s41, 0
	s_mov_b32 m0, s65
	ds_read_b128 v[152:155], v239 offset:32768
	ds_read_b128 v[156:159], v239 offset:33792
	ds_read_b128 v[168:171], v239 offset:34816
	ds_read_b128 v[172:175], v239 offset:35840
	ds_read_b128 v[176:179], v239 offset:36864
	ds_read_b128 v[180:183], v239 offset:37888
	ds_read_b128 v[184:187], v239 offset:38912
	ds_read_b128 v[188:191], v239 offset:39936
	global_load_lds_dwordx4 v218, s[40:41]
	s_mov_b32 m0, s66
	s_nop 0
	global_load_lds_dwordx4 v220, s[40:41]
	s_waitcnt vmcnt(8)
	s_waitcnt lgkmcnt(0)
	s_barrier
	s_setprio 1
	s_waitcnt lgkmcnt(0)
	v_mfma_f32_16x16x32_bf16 v[164:167], v[112:115], v[152:155], v[164:167]
	v_mfma_f32_16x16x32_bf16 v[160:163], v[120:123], v[152:155], v[160:163]
	v_mfma_f32_16x16x32_bf16 v[108:111], v[112:115], v[168:171], v[108:111]
	v_mfma_f32_16x16x32_bf16 v[104:107], v[120:123], v[168:171], v[104:107]
	v_mfma_f32_16x16x32_bf16 v[92:95], v[112:115], v[176:179], v[92:95]
	v_mfma_f32_16x16x32_bf16 v[88:91], v[120:123], v[176:179], v[88:91]
	v_mfma_f32_16x16x32_bf16 v[76:79], v[112:115], v[184:187], v[76:79]
	v_mfma_f32_16x16x32_bf16 v[72:75], v[120:123], v[184:187], v[72:75]
	v_mfma_f32_16x16x32_bf16 v[164:167], v[116:119], v[156:159], v[164:167]
	v_mfma_f32_16x16x32_bf16 v[160:163], v[132:135], v[156:159], v[160:163]
	v_mfma_f32_16x16x32_bf16 v[108:111], v[116:119], v[172:175], v[108:111]
	v_mfma_f32_16x16x32_bf16 v[104:107], v[132:135], v[172:175], v[104:107]
	v_mfma_f32_16x16x32_bf16 v[92:95], v[116:119], v[180:183], v[92:95]
	v_mfma_f32_16x16x32_bf16 v[88:91], v[132:135], v[180:183], v[88:91]
	v_mfma_f32_16x16x32_bf16 v[76:79], v[116:119], v[188:191], v[76:79]
	v_mfma_f32_16x16x32_bf16 v[72:75], v[132:135], v[188:191], v[72:75]
	s_setprio 0
	s_setprio 1
	v_mfma_f32_16x16x32_bf16 v[128:131], v[136:139], v[152:155], v[128:131]
	v_mfma_f32_16x16x32_bf16 v[124:127], v[144:147], v[152:155], v[124:127]
	v_mfma_f32_16x16x32_bf16 v[100:103], v[136:139], v[168:171], v[100:103]
	v_mfma_f32_16x16x32_bf16 v[96:99], v[144:147], v[168:171], v[96:99]
	v_mfma_f32_16x16x32_bf16 v[84:87], v[136:139], v[176:179], v[84:87]
	v_mfma_f32_16x16x32_bf16 v[80:83], v[144:147], v[176:179], v[80:83]
	v_mfma_f32_16x16x32_bf16 v[68:71], v[136:139], v[184:187], v[68:71]
	v_mfma_f32_16x16x32_bf16 v[64:67], v[144:147], v[184:187], v[64:67]
	v_mfma_f32_16x16x32_bf16 v[128:131], v[140:143], v[156:159], v[128:131]
	v_mfma_f32_16x16x32_bf16 v[124:127], v[148:151], v[156:159], v[124:127]
	v_mfma_f32_16x16x32_bf16 v[100:103], v[140:143], v[172:175], v[100:103]
	v_mfma_f32_16x16x32_bf16 v[96:99], v[148:151], v[172:175], v[96:99]
	v_mfma_f32_16x16x32_bf16 v[84:87], v[140:143], v[180:183], v[84:87]
	v_mfma_f32_16x16x32_bf16 v[80:83], v[148:151], v[180:183], v[80:83]
	v_mfma_f32_16x16x32_bf16 v[68:71], v[140:143], v[188:191], v[68:71]
	v_mfma_f32_16x16x32_bf16 v[64:67], v[148:151], v[188:191], v[64:67]
	s_setprio 0
	s_barrier
	s_add_i32 s40, s45, s64
	s_add_u32 s98, s38, 0x80
	s_addc_u32 s99, s39, 0
	s_mov_b32 m0, s40
	ds_read_b128 v[152:155], v239 offset:49152
	ds_read_b128 v[156:159], v239 offset:50176
	ds_read_b128 v[168:171], v239 offset:51200
	ds_read_b128 v[172:175], v239 offset:52224
	ds_read_b128 v[176:179], v239 offset:53248
	ds_read_b128 v[180:183], v239 offset:54272
	ds_read_b128 v[184:187], v239 offset:55296
	ds_read_b128 v[188:191], v239 offset:56320
	global_load_lds_dwordx4 v208, s[98:99]
	s_add_i32 m0, s40, 0x2000
	s_add_u32 s38, s38, 0x40080
	s_addc_u32 s39, s39, 0
	s_add_i32 s40, s48, s64
	global_load_lds_dwordx4 v222, s[98:99]
	s_mov_b32 m0, s40
	s_nop 0
	global_load_lds_dwordx4 v208, s[38:39]
	s_add_i32 m0, s40, 0x2000
	s_nop 0
	global_load_lds_dwordx4 v222, s[38:39]
	s_mov_b32 m0, s74
	s_nop 0
	global_load_lds_dwordx4 v218, s[100:101]
	s_mov_b32 m0, s75
	s_nop 0
	global_load_lds_dwordx4 v220, s[100:101]
	s_waitcnt vmcnt(8)
	s_waitcnt lgkmcnt(0)
	s_barrier
	s_setprio 1
	s_waitcnt lgkmcnt(0)
	v_mfma_f32_16x16x32_bf16 v[60:63], v[112:115], v[152:155], v[60:63]
	v_mfma_f32_16x16x32_bf16 v[56:59], v[120:123], v[152:155], v[56:59]
	v_mfma_f32_16x16x32_bf16 v[44:47], v[112:115], v[168:171], v[44:47]
	v_mfma_f32_16x16x32_bf16 v[40:43], v[120:123], v[168:171], v[40:43]
	v_mfma_f32_16x16x32_bf16 v[28:31], v[112:115], v[176:179], v[28:31]
	v_mfma_f32_16x16x32_bf16 v[24:27], v[120:123], v[176:179], v[24:27]
	v_mfma_f32_16x16x32_bf16 v[12:15], v[112:115], v[184:187], v[12:15]
	v_mfma_f32_16x16x32_bf16 v[8:11], v[120:123], v[184:187], v[8:11]
	v_mfma_f32_16x16x32_bf16 v[60:63], v[116:119], v[156:159], v[60:63]
	v_mfma_f32_16x16x32_bf16 v[56:59], v[132:135], v[156:159], v[56:59]
	v_mfma_f32_16x16x32_bf16 v[44:47], v[116:119], v[172:175], v[44:47]
	v_mfma_f32_16x16x32_bf16 v[40:43], v[132:135], v[172:175], v[40:43]
	v_mfma_f32_16x16x32_bf16 v[28:31], v[116:119], v[180:183], v[28:31]
	v_mfma_f32_16x16x32_bf16 v[24:27], v[132:135], v[180:183], v[24:27]
	v_mfma_f32_16x16x32_bf16 v[12:15], v[116:119], v[188:191], v[12:15]
	v_mfma_f32_16x16x32_bf16 v[8:11], v[132:135], v[188:191], v[8:11]
	s_setprio 0
	s_setprio 1
	v_mfma_f32_16x16x32_bf16 v[52:55], v[136:139], v[152:155], v[52:55]
	v_mfma_f32_16x16x32_bf16 v[48:51], v[144:147], v[152:155], v[48:51]
	v_mfma_f32_16x16x32_bf16 v[36:39], v[136:139], v[168:171], v[36:39]
	v_mfma_f32_16x16x32_bf16 v[32:35], v[144:147], v[168:171], v[32:35]
	v_mfma_f32_16x16x32_bf16 v[20:23], v[136:139], v[176:179], v[20:23]
	v_mfma_f32_16x16x32_bf16 v[16:19], v[144:147], v[176:179], v[16:19]
	v_mfma_f32_16x16x32_bf16 v[4:7], v[136:139], v[184:187], v[4:7]
	v_mfma_f32_16x16x32_bf16 v[0:3], v[144:147], v[184:187], v[0:3]
	v_mfma_f32_16x16x32_bf16 v[52:55], v[140:143], v[156:159], v[52:55]
	v_mfma_f32_16x16x32_bf16 v[48:51], v[148:151], v[156:159], v[48:51]
	v_mfma_f32_16x16x32_bf16 v[36:39], v[140:143], v[172:175], v[36:39]
	v_mfma_f32_16x16x32_bf16 v[32:35], v[148:151], v[172:175], v[32:35]
	v_mfma_f32_16x16x32_bf16 v[20:23], v[140:143], v[180:183], v[20:23]
	v_mfma_f32_16x16x32_bf16 v[16:19], v[148:151], v[180:183], v[16:19]
	v_mfma_f32_16x16x32_bf16 v[4:7], v[140:143], v[188:191], v[4:7]
	v_mfma_f32_16x16x32_bf16 v[0:3], v[148:151], v[188:191], v[0:3]
	s_setprio 0
	s_barrier
	s_add_i32 s44, s44, 2
	s_add_u32 s42, s42, 0x100
	s_addc_u32 s43, s43, 0
	s_add_u32 s34, s34, 0x100
	s_addc_u32 s35, s35, 0
	s_cmp_gt_u32 s44, 13
	s_cbranch_scc0 .LBB0_434
	s_and_b64 vcc, exec, s[30:31]
	s_cbranch_vccz .LBB0_437
	s_barrier

.LBB0_570:
	s_ashr_i32 s29, s28, 31
	s_lshl_b64 s[30:31], s[28:29], 19
	s_add_u32 s30, s62, s30
	s_addc_u32 s31, s63, s31
	s_and_b64 s[34:35], s[36:37], exec
	s_cselect_b32 s3, s31, s43
	s_cselect_b32 s29, s30, s42
	s_ashr_i32 s27, s26, 31
	s_lshl_b64 s[34:35], s[26:27], 19
	s_add_u32 s34, s17, s34
	s_addc_u32 s35, s18, s35
	s_and_b64 s[44:45], s[36:37], exec
	s_cselect_b32 s27, s35, s41
	s_cselect_b32 s39, s34, s40
	s_add_u32 s61, s40, 0x100
	v_lshl_add_u32 v0, s38, 8, v158
	s_addc_u32 s64, s41, 0
	v_ashrrev_i32_e32 v1, 31, v0
	s_add_u32 s40, s42, 0xa000
	v_mov_b32_e32 v8, 0
	v_lshl_add_u64 v[156:157], v[0:1], 2, s[72:73]
	s_addc_u32 s41, s43, 0
	s_mov_b32 s65, -2
	s_mov_b64 s[42:43], 0
	s_add_u32 s44, s40, 0x6000
	s_addc_u32 s45, s41, 0
	s_and_b64 s[42:43], s[42:43], exec
	s_cselect_b32 s46, s29, s44
	s_cselect_b32 s47, s3, s45
	s_cselect_b32 s45, s27, s64
	s_cselect_b32 s44, s39, s61
	s_add_u32 s42, s46, 0x8000
	s_addc_u32 s43, s47, 0
	s_add_i32 s66, 0, 0x10000
	v_add_u32_e32 v169, s66, v159
	s_add_i32 s68, 0, 0x14000
	ds_read_b128 v[170:173], v169
	ds_read_b128 v[174:177], v169 offset:1024
	ds_read_b128 v[178:181], v169 offset:2048
	ds_read_b128 v[182:185], v169 offset:3072
	v_add_u32_e32 v169, s68, v159
	ds_read_b128 v[186:189], v169
	ds_read_b128 v[190:193], v169 offset:1024
	ds_read_b128 v[194:197], v169 offset:2048
	ds_read_b128 v[198:201], v169 offset:3072
	s_add_i32 m0, s48, 0xc000
	ds_read_b128 v[202:205], v160
	ds_read_b128 v[218:221], v160 offset:1024
	ds_read_b128 v[222:225], v160 offset:2048
	ds_read_b128 v[226:229], v160 offset:3072
	ds_read_b128 v[230:233], v160 offset:4096
	ds_read_b128 v[234:237], v160 offset:5120
	ds_read_b128 v[238:241], v160 offset:6144
	ds_read_b128 v[246:249], v160 offset:7168
	global_load_lds_dwordx4 v152, s[40:41]
	s_add_i32 m0, s48, 0xe000
	s_nop 0
	global_load_lds_dwordx4 v154, s[40:41]
	s_waitcnt vmcnt(8)
	s_waitcnt lgkmcnt(0)
	s_barrier
	s_setprio 1
	s_waitcnt lgkmcnt(0)
	v_mfma_f32_16x16x32_bf16 v[116:119], v[170:173], v[202:205], 0
	v_mfma_f32_16x16x32_bf16 v[124:127], v[178:181], v[202:205], 0
	v_mfma_f32_16x16x32_bf16 v[100:103], v[170:173], v[222:225], 0
	v_mfma_f32_16x16x32_bf16 v[108:111], v[178:181], v[222:225], 0
	v_mfma_f32_16x16x32_bf16 v[84:87], v[170:173], v[230:233], 0
	v_mfma_f32_16x16x32_bf16 v[92:95], v[178:181], v[230:233], 0
	v_mfma_f32_16x16x32_bf16 v[68:71], v[170:173], v[238:241], 0
	v_mfma_f32_16x16x32_bf16 v[76:79], v[178:181], v[238:241], 0
	v_mfma_f32_16x16x32_bf16 v[116:119], v[174:177], v[218:221], v[116:119]
	v_mfma_f32_16x16x32_bf16 v[124:127], v[182:185], v[218:221], v[124:127]
	v_mfma_f32_16x16x32_bf16 v[100:103], v[174:177], v[226:229], v[100:103]
	v_mfma_f32_16x16x32_bf16 v[108:111], v[182:185], v[226:229], v[108:111]
	v_mfma_f32_16x16x32_bf16 v[84:87], v[174:177], v[234:237], v[84:87]
	v_mfma_f32_16x16x32_bf16 v[92:95], v[182:185], v[234:237], v[92:95]
	v_mfma_f32_16x16x32_bf16 v[68:71], v[174:177], v[246:249], v[68:71]
	v_mfma_f32_16x16x32_bf16 v[76:79], v[182:185], v[246:249], v[76:79]
	s_setprio 0
	s_setprio 1
	v_mfma_f32_16x16x32_bf16 v[112:115], v[186:189], v[202:205], 0
	v_mfma_f32_16x16x32_bf16 v[120:123], v[194:197], v[202:205], 0
	v_mfma_f32_16x16x32_bf16 v[96:99], v[186:189], v[222:225], 0
	v_mfma_f32_16x16x32_bf16 v[104:107], v[194:197], v[222:225], 0
	v_mfma_f32_16x16x32_bf16 v[80:83], v[186:189], v[230:233], 0
	v_mfma_f32_16x16x32_bf16 v[88:91], v[194:197], v[230:233], 0
	v_mfma_f32_16x16x32_bf16 v[64:67], v[186:189], v[238:241], 0
	v_mfma_f32_16x16x32_bf16 v[72:75], v[194:197], v[238:241], 0
	v_mfma_f32_16x16x32_bf16 v[112:115], v[190:193], v[218:221], v[112:115]
	v_mfma_f32_16x16x32_bf16 v[120:123], v[198:201], v[218:221], v[120:123]
	v_mfma_f32_16x16x32_bf16 v[96:99], v[190:193], v[226:229], v[96:99]
	v_mfma_f32_16x16x32_bf16 v[104:107], v[198:201], v[226:229], v[104:107]
	v_mfma_f32_16x16x32_bf16 v[80:83], v[190:193], v[234:237], v[80:83]
	v_mfma_f32_16x16x32_bf16 v[88:91], v[198:201], v[234:237], v[88:91]
	v_mfma_f32_16x16x32_bf16 v[64:67], v[190:193], v[246:249], v[64:67]
	v_mfma_f32_16x16x32_bf16 v[72:75], v[198:201], v[246:249], v[72:75]
	s_setprio 0
	s_barrier
	s_add_i32 s66, s66, s19
	s_mov_b32 m0, s66
	ds_read_b128 v[202:205], v160 offset:16384
	ds_read_b128 v[218:221], v160 offset:17408
	ds_read_b128 v[222:225], v160 offset:18432
	ds_read_b128 v[226:229], v160 offset:19456
	ds_read_b128 v[230:233], v160 offset:20480
	ds_read_b128 v[234:237], v160 offset:21504
	ds_read_b128 v[238:241], v160 offset:22528
	ds_read_b128 v[246:249], v160 offset:23552
	global_load_lds_dwordx4 v132, s[44:45]
	s_add_i32 m0, s66, 0x2000
	s_add_u32 s66, s44, 0x40000
	s_addc_u32 s67, s45, 0
	s_add_i32 s68, s68, s19
	global_load_lds_dwordx4 v128, s[44:45]
	s_mov_b32 m0, s68
	s_nop 0
	global_load_lds_dwordx4 v132, s[66:67]
	s_add_i32 m0, s68, 0x2000
	s_nop 0
	global_load_lds_dwordx4 v128, s[66:67]
	s_mov_b32 m0, s48
	s_nop 0
	global_load_lds_dwordx4 v134, s[46:47]
	s_mov_b32 m0, s49
	s_nop 0
	global_load_lds_dwordx4 v130, s[46:47]
	s_waitcnt vmcnt(8)
	s_waitcnt lgkmcnt(0)
	s_barrier
	s_setprio 1
	s_waitcnt lgkmcnt(0)
	v_mfma_f32_16x16x32_bf16 v[52:55], v[170:173], v[202:205], 0
	v_mfma_f32_16x16x32_bf16 v[60:63], v[178:181], v[202:205], 0
	v_mfma_f32_16x16x32_bf16 v[36:39], v[170:173], v[222:225], 0
	v_mfma_f32_16x16x32_bf16 v[44:47], v[178:181], v[222:225], 0
	v_mfma_f32_16x16x32_bf16 v[20:23], v[170:173], v[230:233], 0
	v_mfma_f32_16x16x32_bf16 v[28:31], v[178:181], v[230:233], 0
	v_mfma_f32_16x16x32_bf16 v[4:7], v[170:173], v[238:241], 0
	v_mfma_f32_16x16x32_bf16 v[12:15], v[178:181], v[238:241], 0
	v_mfma_f32_16x16x32_bf16 v[52:55], v[174:177], v[218:221], v[52:55]
	v_mfma_f32_16x16x32_bf16 v[60:63], v[182:185], v[218:221], v[60:63]
	v_mfma_f32_16x16x32_bf16 v[36:39], v[174:177], v[226:229], v[36:39]
	v_mfma_f32_16x16x32_bf16 v[44:47], v[182:185], v[226:229], v[44:47]
	v_mfma_f32_16x16x32_bf16 v[20:23], v[174:177], v[234:237], v[20:23]
	v_mfma_f32_16x16x32_bf16 v[28:31], v[182:185], v[234:237], v[28:31]
	v_mfma_f32_16x16x32_bf16 v[4:7], v[174:177], v[246:249], v[4:7]
	v_mfma_f32_16x16x32_bf16 v[12:15], v[182:185], v[246:249], v[12:15]
	s_setprio 0
	s_setprio 1
	v_mfma_f32_16x16x32_bf16 v[48:51], v[186:189], v[202:205], 0
	v_mfma_f32_16x16x32_bf16 v[56:59], v[194:197], v[202:205], 0
	v_mfma_f32_16x16x32_bf16 v[32:35], v[186:189], v[222:225], 0
	v_mfma_f32_16x16x32_bf16 v[40:43], v[194:197], v[222:225], 0
	v_mfma_f32_16x16x32_bf16 v[16:19], v[186:189], v[230:233], 0
	v_mfma_f32_16x16x32_bf16 v[24:27], v[194:197], v[230:233], 0
	v_mfma_f32_16x16x32_bf16 v[0:3], v[186:189], v[238:241], 0
	v_mfma_f32_16x16x32_bf16 v[8:11], v[194:197], v[238:241], 0
	v_mfma_f32_16x16x32_bf16 v[48:51], v[190:193], v[218:221], v[48:51]
	v_mfma_f32_16x16x32_bf16 v[56:59], v[198:201], v[218:221], v[56:59]
	v_mfma_f32_16x16x32_bf16 v[32:35], v[190:193], v[226:229], v[32:35]
	v_mfma_f32_16x16x32_bf16 v[40:43], v[198:201], v[226:229], v[40:43]
	v_mfma_f32_16x16x32_bf16 v[16:19], v[190:193], v[234:237], v[16:19]
	v_mfma_f32_16x16x32_bf16 v[24:27], v[198:201], v[234:237], v[24:27]
	v_mfma_f32_16x16x32_bf16 v[0:3], v[190:193], v[246:249], v[0:3]
	v_mfma_f32_16x16x32_bf16 v[8:11], v[198:201], v[246:249], v[8:11]
	s_setprio 0
	s_barrier
	s_branch .Lgu_mid
.LBB0_571:
	s_add_u32 s44, s40, 0x6000
	s_addc_u32 s45, s41, 0
	s_and_b64 s[42:43], s[42:43], exec
	s_cselect_b32 s46, s29, s44
	s_cselect_b32 s47, s3, s45
	s_cselect_b32 s45, s27, s64
	s_cselect_b32 s44, s39, s61
	s_add_u32 s42, s46, 0x8000
	s_addc_u32 s43, s47, 0
	s_add_i32 s66, 0, 0x10000
	v_add_u32_e32 v169, s66, v159
	s_add_i32 s68, 0, 0x14000
	ds_read_b128 v[170:173], v169
	ds_read_b128 v[174:177], v169 offset:1024
	ds_read_b128 v[178:181], v169 offset:2048
	ds_read_b128 v[182:185], v169 offset:3072
	v_add_u32_e32 v169, s68, v159
	ds_read_b128 v[186:189], v169
	ds_read_b128 v[190:193], v169 offset:1024
	ds_read_b128 v[194:197], v169 offset:2048
	ds_read_b128 v[198:201], v169 offset:3072
	s_add_i32 m0, s48, 0xc000
	ds_read_b128 v[202:205], v160
	ds_read_b128 v[218:221], v160 offset:1024
	ds_read_b128 v[222:225], v160 offset:2048
	ds_read_b128 v[226:229], v160 offset:3072
	ds_read_b128 v[230:233], v160 offset:4096
	ds_read_b128 v[234:237], v160 offset:5120
	ds_read_b128 v[238:241], v160 offset:6144
	ds_read_b128 v[246:249], v160 offset:7168
	global_load_lds_dwordx4 v152, s[40:41]
	s_add_i32 m0, s48, 0xe000
	s_nop 0
	global_load_lds_dwordx4 v154, s[40:41]
	s_waitcnt vmcnt(8)
	s_waitcnt lgkmcnt(0)
	s_barrier
	s_setprio 1
	s_waitcnt lgkmcnt(0)
	v_mfma_f32_16x16x32_bf16 v[116:119], v[170:173], v[202:205], v[116:119]
	v_mfma_f32_16x16x32_bf16 v[124:127], v[178:181], v[202:205], v[124:127]
	v_mfma_f32_16x16x32_bf16 v[100:103], v[170:173], v[222:225], v[100:103]
	v_mfma_f32_16x16x32_bf16 v[108:111], v[178:181], v[222:225], v[108:111]
	v_mfma_f32_16x16x32_bf16 v[84:87], v[170:173], v[230:233], v[84:87]
	v_mfma_f32_16x16x32_bf16 v[92:95], v[178:181], v[230:233], v[92:95]
	v_mfma_f32_16x16x32_bf16 v[68:71], v[170:173], v[238:241], v[68:71]
	v_mfma_f32_16x16x32_bf16 v[76:79], v[178:181], v[238:241], v[76:79]
	v_mfma_f32_16x16x32_bf16 v[116:119], v[174:177], v[218:221], v[116:119]
	v_mfma_f32_16x16x32_bf16 v[124:127], v[182:185], v[218:221], v[124:127]
	v_mfma_f32_16x16x32_bf16 v[100:103], v[174:177], v[226:229], v[100:103]
	v_mfma_f32_16x16x32_bf16 v[108:111], v[182:185], v[226:229], v[108:111]
	v_mfma_f32_16x16x32_bf16 v[84:87], v[174:177], v[234:237], v[84:87]
	v_mfma_f32_16x16x32_bf16 v[92:95], v[182:185], v[234:237], v[92:95]
	v_mfma_f32_16x16x32_bf16 v[68:71], v[174:177], v[246:249], v[68:71]
	v_mfma_f32_16x16x32_bf16 v[76:79], v[182:185], v[246:249], v[76:79]
	s_setprio 0
	s_setprio 1
	v_mfma_f32_16x16x32_bf16 v[112:115], v[186:189], v[202:205], v[112:115]
	v_mfma_f32_16x16x32_bf16 v[120:123], v[194:197], v[202:205], v[120:123]
	v_mfma_f32_16x16x32_bf16 v[96:99], v[186:189], v[222:225], v[96:99]
	v_mfma_f32_16x16x32_bf16 v[104:107], v[194:197], v[222:225], v[104:107]
	v_mfma_f32_16x16x32_bf16 v[80:83], v[186:189], v[230:233], v[80:83]
	v_mfma_f32_16x16x32_bf16 v[88:91], v[194:197], v[230:233], v[88:91]
	v_mfma_f32_16x16x32_bf16 v[64:67], v[186:189], v[238:241], v[64:67]
	v_mfma_f32_16x16x32_bf16 v[72:75], v[194:197], v[238:241], v[72:75]
	v_mfma_f32_16x16x32_bf16 v[112:115], v[190:193], v[218:221], v[112:115]
	v_mfma_f32_16x16x32_bf16 v[120:123], v[198:201], v[218:221], v[120:123]
	v_mfma_f32_16x16x32_bf16 v[96:99], v[190:193], v[226:229], v[96:99]
	v_mfma_f32_16x16x32_bf16 v[104:107], v[198:201], v[226:229], v[104:107]
	v_mfma_f32_16x16x32_bf16 v[80:83], v[190:193], v[234:237], v[80:83]
	v_mfma_f32_16x16x32_bf16 v[88:91], v[198:201], v[234:237], v[88:91]
	v_mfma_f32_16x16x32_bf16 v[64:67], v[190:193], v[246:249], v[64:67]
	v_mfma_f32_16x16x32_bf16 v[72:75], v[198:201], v[246:249], v[72:75]
	s_setprio 0
	s_barrier
	s_add_i32 s66, s66, s19
	s_mov_b32 m0, s66
	ds_read_b128 v[202:205], v160 offset:16384
	ds_read_b128 v[218:221], v160 offset:17408
	ds_read_b128 v[222:225], v160 offset:18432
	ds_read_b128 v[226:229], v160 offset:19456
	ds_read_b128 v[230:233], v160 offset:20480
	ds_read_b128 v[234:237], v160 offset:21504
	ds_read_b128 v[238:241], v160 offset:22528
	ds_read_b128 v[246:249], v160 offset:23552
	global_load_lds_dwordx4 v132, s[44:45]
	s_add_i32 m0, s66, 0x2000
	s_add_u32 s66, s44, 0x40000
	s_addc_u32 s67, s45, 0
	s_add_i32 s68, s68, s19
	global_load_lds_dwordx4 v128, s[44:45]
	s_mov_b32 m0, s68
	s_nop 0
	global_load_lds_dwordx4 v132, s[66:67]
	s_add_i32 m0, s68, 0x2000
	s_nop 0
	global_load_lds_dwordx4 v128, s[66:67]
	s_mov_b32 m0, s48
	s_nop 0
	global_load_lds_dwordx4 v134, s[46:47]
	s_mov_b32 m0, s49
	s_nop 0
	global_load_lds_dwordx4 v130, s[46:47]
	s_waitcnt vmcnt(8)
	s_waitcnt lgkmcnt(0)
	s_barrier
	s_setprio 1
	s_waitcnt lgkmcnt(0)
	v_mfma_f32_16x16x32_bf16 v[52:55], v[170:173], v[202:205], v[52:55]
	v_mfma_f32_16x16x32_bf16 v[60:63], v[178:181], v[202:205], v[60:63]
	v_mfma_f32_16x16x32_bf16 v[36:39], v[170:173], v[222:225], v[36:39]
	v_mfma_f32_16x16x32_bf16 v[44:47], v[178:181], v[222:225], v[44:47]
	v_mfma_f32_16x16x32_bf16 v[20:23], v[170:173], v[230:233], v[20:23]
	v_mfma_f32_16x16x32_bf16 v[28:31], v[178:181], v[230:233], v[28:31]
	v_mfma_f32_16x16x32_bf16 v[4:7], v[170:173], v[238:241], v[4:7]
	v_mfma_f32_16x16x32_bf16 v[12:15], v[178:181], v[238:241], v[12:15]
	v_mfma_f32_16x16x32_bf16 v[52:55], v[174:177], v[218:221], v[52:55]
	v_mfma_f32_16x16x32_bf16 v[60:63], v[182:185], v[218:221], v[60:63]
	v_mfma_f32_16x16x32_bf16 v[36:39], v[174:177], v[226:229], v[36:39]
	v_mfma_f32_16x16x32_bf16 v[44:47], v[182:185], v[226:229], v[44:47]
	v_mfma_f32_16x16x32_bf16 v[20:23], v[174:177], v[234:237], v[20:23]
	v_mfma_f32_16x16x32_bf16 v[28:31], v[182:185], v[234:237], v[28:31]
	v_mfma_f32_16x16x32_bf16 v[4:7], v[174:177], v[246:249], v[4:7]
	v_mfma_f32_16x16x32_bf16 v[12:15], v[182:185], v[246:249], v[12:15]
	s_setprio 0
	s_setprio 1
	v_mfma_f32_16x16x32_bf16 v[48:51], v[186:189], v[202:205], v[48:51]
	v_mfma_f32_16x16x32_bf16 v[56:59], v[194:197], v[202:205], v[56:59]
	v_mfma_f32_16x16x32_bf16 v[32:35], v[186:189], v[222:225], v[32:35]
	v_mfma_f32_16x16x32_bf16 v[40:43], v[194:197], v[222:225], v[40:43]
	v_mfma_f32_16x16x32_bf16 v[16:19], v[186:189], v[230:233], v[16:19]
	v_mfma_f32_16x16x32_bf16 v[24:27], v[194:197], v[230:233], v[24:27]
	v_mfma_f32_16x16x32_bf16 v[0:3], v[186:189], v[238:241], v[0:3]
	v_mfma_f32_16x16x32_bf16 v[8:11], v[194:197], v[238:241], v[8:11]
	v_mfma_f32_16x16x32_bf16 v[48:51], v[190:193], v[218:221], v[48:51]
	v_mfma_f32_16x16x32_bf16 v[56:59], v[198:201], v[218:221], v[56:59]
	v_mfma_f32_16x16x32_bf16 v[32:35], v[190:193], v[226:229], v[32:35]
	v_mfma_f32_16x16x32_bf16 v[40:43], v[198:201], v[226:229], v[40:43]
	v_mfma_f32_16x16x32_bf16 v[16:19], v[190:193], v[234:237], v[16:19]
	v_mfma_f32_16x16x32_bf16 v[24:27], v[198:201], v[234:237], v[24:27]
	v_mfma_f32_16x16x32_bf16 v[0:3], v[190:193], v[246:249], v[0:3]
	v_mfma_f32_16x16x32_bf16 v[8:11], v[198:201], v[246:249], v[8:11]
	s_setprio 0
	s_barrier
.Lgu_mid:
	s_add_i32 s66, 0, 0x18000
	v_add_u32_e32 v169, s66, v159
	s_add_i32 s67, 0, 0x1c000
	ds_read_b128 v[170:173], v169
	ds_read_b128 v[174:177], v169 offset:1024
	ds_read_b128 v[178:181], v169 offset:2048
	ds_read_b128 v[182:185], v169 offset:3072
	v_add_u32_e32 v169, s67, v159
	ds_read_b128 v[186:189], v169
	ds_read_b128 v[190:193], v169 offset:1024
	ds_read_b128 v[194:197], v169 offset:2048
	ds_read_b128 v[198:201], v169 offset:3072
	s_add_u32 s46, s46, 0x2000
	s_addc_u32 s47, s47, 0
	s_mov_b32 m0, s52
	ds_read_b128 v[202:205], v160 offset:32768
	ds_read_b128 v[218:221], v160 offset:33792
	ds_read_b128 v[222:225], v160 offset:34816
	ds_read_b128 v[226:229], v160 offset:35840
	ds_read_b128 v[230:233], v160 offset:36864
	ds_read_b128 v[234:237], v160 offset:37888
	ds_read_b128 v[238:241], v160 offset:38912
	ds_read_b128 v[246:249], v160 offset:39936
	global_load_lds_dwordx4 v134, s[46:47]
	s_mov_b32 m0, s53
	s_nop 0
	global_load_lds_dwordx4 v130, s[46:47]
	s_waitcnt vmcnt(8)
	s_waitcnt lgkmcnt(0)
	s_barrier
	s_setprio 1
	s_waitcnt lgkmcnt(0)
	v_mfma_f32_16x16x32_bf16 v[116:119], v[170:173], v[202:205], v[116:119]
	v_mfma_f32_16x16x32_bf16 v[124:127], v[178:181], v[202:205], v[124:127]
	v_mfma_f32_16x16x32_bf16 v[100:103], v[170:173], v[222:225], v[100:103]
	v_mfma_f32_16x16x32_bf16 v[108:111], v[178:181], v[222:225], v[108:111]
	v_mfma_f32_16x16x32_bf16 v[84:87], v[170:173], v[230:233], v[84:87]
	v_mfma_f32_16x16x32_bf16 v[92:95], v[178:181], v[230:233], v[92:95]
	v_mfma_f32_16x16x32_bf16 v[68:71], v[170:173], v[238:241], v[68:71]
	v_mfma_f32_16x16x32_bf16 v[76:79], v[178:181], v[238:241], v[76:79]
	v_mfma_f32_16x16x32_bf16 v[116:119], v[174:177], v[218:221], v[116:119]
	v_mfma_f32_16x16x32_bf16 v[124:127], v[182:185], v[218:221], v[124:127]
	v_mfma_f32_16x16x32_bf16 v[100:103], v[174:177], v[226:229], v[100:103]
	v_mfma_f32_16x16x32_bf16 v[108:111], v[182:185], v[226:229], v[108:111]
	v_mfma_f32_16x16x32_bf16 v[84:87], v[174:177], v[234:237], v[84:87]
	v_mfma_f32_16x16x32_bf16 v[92:95], v[182:185], v[234:237], v[92:95]
	v_mfma_f32_16x16x32_bf16 v[68:71], v[174:177], v[246:249], v[68:71]
	v_mfma_f32_16x16x32_bf16 v[76:79], v[182:185], v[246:249], v[76:79]
	s_setprio 0
	s_setprio 1
	v_mfma_f32_16x16x32_bf16 v[112:115], v[186:189], v[202:205], v[112:115]
	v_mfma_f32_16x16x32_bf16 v[120:123], v[194:197], v[202:205], v[120:123]
	v_mfma_f32_16x16x32_bf16 v[96:99], v[186:189], v[222:225], v[96:99]
	v_mfma_f32_16x16x32_bf16 v[104:107], v[194:197], v[222:225], v[104:107]
	v_mfma_f32_16x16x32_bf16 v[80:83], v[186:189], v[230:233], v[80:83]
	v_mfma_f32_16x16x32_bf16 v[88:91], v[194:197], v[230:233], v[88:91]
	v_mfma_f32_16x16x32_bf16 v[64:67], v[186:189], v[238:241], v[64:67]
	v_mfma_f32_16x16x32_bf16 v[72:75], v[194:197], v[238:241], v[72:75]
	v_mfma_f32_16x16x32_bf16 v[112:115], v[190:193], v[218:221], v[112:115]
	v_mfma_f32_16x16x32_bf16 v[120:123], v[198:201], v[218:221], v[120:123]
	v_mfma_f32_16x16x32_bf16 v[96:99], v[190:193], v[226:229], v[96:99]
	v_mfma_f32_16x16x32_bf16 v[104:107], v[198:201], v[226:229], v[104:107]
	v_mfma_f32_16x16x32_bf16 v[80:83], v[190:193], v[234:237], v[80:83]
	v_mfma_f32_16x16x32_bf16 v[88:91], v[198:201], v[234:237], v[88:91]
	v_mfma_f32_16x16x32_bf16 v[64:67], v[190:193], v[246:249], v[64:67]
	v_mfma_f32_16x16x32_bf16 v[72:75], v[198:201], v[246:249], v[72:75]
	s_setprio 0
	s_barrier
	s_add_i32 s46, s66, s19
	s_add_u32 s98, s44, 0x80
	s_addc_u32 s99, s45, 0
	s_mov_b32 m0, s46
	ds_read_b128 v[202:205], v160 offset:49152
	ds_read_b128 v[218:221], v160 offset:50176
	ds_read_b128 v[222:225], v160 offset:51200
	ds_read_b128 v[226:229], v160 offset:52224
	ds_read_b128 v[230:233], v160 offset:53248
	ds_read_b128 v[234:237], v160 offset:54272
	ds_read_b128 v[238:241], v160 offset:55296
	ds_read_b128 v[246:249], v160 offset:56320
	global_load_lds_dwordx4 v132, s[98:99]
	s_add_i32 m0, s46, 0x2000
	s_add_u32 s44, s44, 0x40080
	s_addc_u32 s45, s45, 0
	s_add_i32 s46, s67, s19
	global_load_lds_dwordx4 v128, s[98:99]
	s_mov_b32 m0, s46
	s_nop 0
	global_load_lds_dwordx4 v132, s[44:45]
	s_add_i32 m0, s46, 0x2000
	s_nop 0
	global_load_lds_dwordx4 v128, s[44:45]
	s_mov_b32 m0, s0
	s_nop 0
	global_load_lds_dwordx4 v134, s[42:43]
	s_mov_b32 m0, s56
	s_nop 0
	global_load_lds_dwordx4 v130, s[42:43]
	s_waitcnt vmcnt(8)
	s_waitcnt lgkmcnt(0)
	s_barrier
	s_setprio 1
	s_waitcnt lgkmcnt(0)
	v_mfma_f32_16x16x32_bf16 v[52:55], v[170:173], v[202:205], v[52:55]
	v_mfma_f32_16x16x32_bf16 v[60:63], v[178:181], v[202:205], v[60:63]
	v_mfma_f32_16x16x32_bf16 v[36:39], v[170:173], v[222:225], v[36:39]
	v_mfma_f32_16x16x32_bf16 v[44:47], v[178:181], v[222:225], v[44:47]
	v_mfma_f32_16x16x32_bf16 v[20:23], v[170:173], v[230:233], v[20:23]
	v_mfma_f32_16x16x32_bf16 v[28:31], v[178:181], v[230:233], v[28:31]
	v_mfma_f32_16x16x32_bf16 v[4:7], v[170:173], v[238:241], v[4:7]
	v_mfma_f32_16x16x32_bf16 v[12:15], v[178:181], v[238:241], v[12:15]
	v_mfma_f32_16x16x32_bf16 v[52:55], v[174:177], v[218:221], v[52:55]
	v_mfma_f32_16x16x32_bf16 v[60:63], v[182:185], v[218:221], v[60:63]
	v_mfma_f32_16x16x32_bf16 v[36:39], v[174:177], v[226:229], v[36:39]
	v_mfma_f32_16x16x32_bf16 v[44:47], v[182:185], v[226:229], v[44:47]
	v_mfma_f32_16x16x32_bf16 v[20:23], v[174:177], v[234:237], v[20:23]
	v_mfma_f32_16x16x32_bf16 v[28:31], v[182:185], v[234:237], v[28:31]
	v_mfma_f32_16x16x32_bf16 v[4:7], v[174:177], v[246:249], v[4:7]
	v_mfma_f32_16x16x32_bf16 v[12:15], v[182:185], v[246:249], v[12:15]
	s_setprio 0
	s_setprio 1
	v_mfma_f32_16x16x32_bf16 v[48:51], v[186:189], v[202:205], v[48:51]
	v_mfma_f32_16x16x32_bf16 v[56:59], v[194:197], v[202:205], v[56:59]
	v_mfma_f32_16x16x32_bf16 v[32:35], v[186:189], v[222:225], v[32:35]
	v_mfma_f32_16x16x32_bf16 v[40:43], v[194:197], v[222:225], v[40:43]
	v_mfma_f32_16x16x32_bf16 v[16:19], v[186:189], v[230:233], v[16:19]
	v_mfma_f32_16x16x32_bf16 v[24:27], v[194:197], v[230:233], v[24:27]
	v_mfma_f32_16x16x32_bf16 v[0:3], v[186:189], v[238:241], v[0:3]
	v_mfma_f32_16x16x32_bf16 v[8:11], v[194:197], v[238:241], v[8:11]
	v_mfma_f32_16x16x32_bf16 v[48:51], v[190:193], v[218:221], v[48:51]
	v_mfma_f32_16x16x32_bf16 v[56:59], v[198:201], v[218:221], v[56:59]
	v_mfma_f32_16x16x32_bf16 v[32:35], v[190:193], v[226:229], v[32:35]
	v_mfma_f32_16x16x32_bf16 v[40:43], v[198:201], v[226:229], v[40:43]
	v_mfma_f32_16x16x32_bf16 v[16:19], v[190:193], v[234:237], v[16:19]
	v_mfma_f32_16x16x32_bf16 v[24:27], v[198:201], v[234:237], v[24:27]
	v_mfma_f32_16x16x32_bf16 v[0:3], v[190:193], v[246:249], v[0:3]
	v_mfma_f32_16x16x32_bf16 v[8:11], v[198:201], v[246:249], v[8:11]
	s_setprio 0
	s_barrier
	s_add_i32 s65, s65, 2
	s_add_u32 s61, s61, 0x100
	s_addc_u32 s64, s64, 0
	s_add_u32 s40, s40, 0x10000
	s_addc_u32 s41, s41, 0
	s_cmp_gt_u32 s65, 13
	s_cbranch_scc1 .LBB0_574

.LBB0_653:
	s_add_u32 s34, s34, 0xa000
	s_addc_u32 s35, s35, 0
	s_add_u32 s2, s78, 0x100
	v_mov_b32_e32 v0, 0
	s_addc_u32 s3, s79, 0
	s_mov_b32 s27, -2
	s_waitcnt lgkmcnt(0)
	s_add_u32 s38, s34, 0x6000
	s_addc_u32 s39, s35, 0
	s_cmp_eq_u32 s27, 40
	s_cselect_b32 s42, s56, s38
	s_cselect_b32 s43, s57, s39
	s_cselect_b32 s40, s60, s2
	s_cselect_b32 s41, s61, s3
	s_add_u32 s38, s42, 0x8000
	s_addc_u32 s39, s43, 0
	s_add_i32 s44, 0, 0x10000
	s_add_i32 s46, 0, 0x14000
	v_add_u32_e32 v124, s44, v248
	v_add_u32_e32 v144, s46, v248
	ds_read_b128 v[88:91], v124
	ds_read_b128 v[100:103], v124 offset:1024
	ds_read_b128 v[112:115], v124 offset:2048
	ds_read_b128 v[124:127], v124 offset:3072
	ds_read_b128 v[128:131], v144
	ds_read_b128 v[132:135], v144 offset:1024
	ds_read_b128 v[136:139], v144 offset:2048
	ds_read_b128 v[144:147], v144 offset:3072
	s_add_i32 m0, s95, 0xc000
	ds_read_b128 v[152:155], v249
	ds_read_b128 v[156:159], v249 offset:1024
	ds_read_b128 v[168:171], v249 offset:2048
	ds_read_b128 v[172:175], v249 offset:3072
	ds_read_b128 v[176:179], v249 offset:4096
	ds_read_b128 v[180:183], v249 offset:5120
	ds_read_b128 v[184:187], v249 offset:6144
	ds_read_b128 v[188:191], v249 offset:7168
	global_load_lds_dwordx4 v224, s[34:35]
	s_add_i32 m0, s95, 0xe000
	s_nop 0
	global_load_lds_dwordx4 v226, s[34:35]
	s_waitcnt vmcnt(8)
	s_waitcnt lgkmcnt(0)
	s_barrier
	s_setprio 1
	s_waitcnt lgkmcnt(0)
	v_mfma_f32_16x16x32_bf16 v[164:167], v[88:91], v[152:155], 0
	v_mfma_f32_16x16x32_bf16 v[160:163], v[112:115], v[152:155], 0
	v_mfma_f32_16x16x32_bf16 v[120:123], v[88:91], v[168:171], 0
	v_mfma_f32_16x16x32_bf16 v[116:119], v[112:115], v[168:171], 0
	v_mfma_f32_16x16x32_bf16 v[96:99], v[88:91], v[176:179], 0
	v_mfma_f32_16x16x32_bf16 v[92:95], v[112:115], v[176:179], 0
	v_mfma_f32_16x16x32_bf16 v[76:79], v[88:91], v[184:187], 0
	v_mfma_f32_16x16x32_bf16 v[72:75], v[112:115], v[184:187], 0
	v_mfma_f32_16x16x32_bf16 v[164:167], v[100:103], v[156:159], v[164:167]
	v_mfma_f32_16x16x32_bf16 v[160:163], v[124:127], v[156:159], v[160:163]
	v_mfma_f32_16x16x32_bf16 v[120:123], v[100:103], v[172:175], v[120:123]
	v_mfma_f32_16x16x32_bf16 v[116:119], v[124:127], v[172:175], v[116:119]
	v_mfma_f32_16x16x32_bf16 v[96:99], v[100:103], v[180:183], v[96:99]
	v_mfma_f32_16x16x32_bf16 v[92:95], v[124:127], v[180:183], v[92:95]
	v_mfma_f32_16x16x32_bf16 v[76:79], v[100:103], v[188:191], v[76:79]
	v_mfma_f32_16x16x32_bf16 v[72:75], v[124:127], v[188:191], v[72:75]
	s_setprio 0
	s_setprio 1
	v_mfma_f32_16x16x32_bf16 v[148:151], v[128:131], v[152:155], 0
	v_mfma_f32_16x16x32_bf16 v[140:143], v[136:139], v[152:155], 0
	v_mfma_f32_16x16x32_bf16 v[108:111], v[128:131], v[168:171], 0
	v_mfma_f32_16x16x32_bf16 v[104:107], v[136:139], v[168:171], 0
	v_mfma_f32_16x16x32_bf16 v[84:87], v[128:131], v[176:179], 0
	v_mfma_f32_16x16x32_bf16 v[80:83], v[136:139], v[176:179], 0
	v_mfma_f32_16x16x32_bf16 v[68:71], v[128:131], v[184:187], 0
	v_mfma_f32_16x16x32_bf16 v[64:67], v[136:139], v[184:187], 0
	v_mfma_f32_16x16x32_bf16 v[148:151], v[132:135], v[156:159], v[148:151]
	v_mfma_f32_16x16x32_bf16 v[140:143], v[144:147], v[156:159], v[140:143]
	v_mfma_f32_16x16x32_bf16 v[108:111], v[132:135], v[172:175], v[108:111]
	v_mfma_f32_16x16x32_bf16 v[104:107], v[144:147], v[172:175], v[104:107]
	v_mfma_f32_16x16x32_bf16 v[84:87], v[132:135], v[180:183], v[84:87]
	v_mfma_f32_16x16x32_bf16 v[80:83], v[144:147], v[180:183], v[80:83]
	v_mfma_f32_16x16x32_bf16 v[68:71], v[132:135], v[188:191], v[68:71]
	v_mfma_f32_16x16x32_bf16 v[64:67], v[144:147], v[188:191], v[64:67]
	s_setprio 0
	s_barrier
	s_add_i32 s44, s44, s94
	s_mov_b32 m0, s44
	ds_read_b128 v[152:155], v249 offset:16384
	ds_read_b128 v[156:159], v249 offset:17408
	ds_read_b128 v[168:171], v249 offset:18432
	ds_read_b128 v[172:175], v249 offset:19456
	ds_read_b128 v[176:179], v249 offset:20480
	ds_read_b128 v[180:183], v249 offset:21504
	ds_read_b128 v[184:187], v249 offset:22528
	ds_read_b128 v[188:191], v249 offset:23552
	global_load_lds_dwordx4 v208, s[40:41]
	s_add_i32 m0, s44, 0x2000
	s_add_u32 s44, s40, 0xb0000
	s_addc_u32 s45, s41, 0
	s_add_i32 s46, s46, s94
	global_load_lds_dwordx4 v222, s[40:41]
	s_mov_b32 m0, s46
	s_nop 0
	global_load_lds_dwordx4 v208, s[44:45]
	s_add_i32 m0, s46, 0x2000
	s_nop 0
	global_load_lds_dwordx4 v222, s[44:45]
	s_mov_b32 m0, s95
	s_nop 0
	global_load_lds_dwordx4 v218, s[42:43]
	s_mov_b32 m0, s18
	s_nop 0
	global_load_lds_dwordx4 v220, s[42:43]
	s_waitcnt vmcnt(8)
	s_waitcnt lgkmcnt(0)
	s_barrier
	s_setprio 1
	s_waitcnt lgkmcnt(0)
	v_mfma_f32_16x16x32_bf16 v[60:63], v[88:91], v[152:155], 0
	v_mfma_f32_16x16x32_bf16 v[56:59], v[112:115], v[152:155], 0
	v_mfma_f32_16x16x32_bf16 v[44:47], v[88:91], v[168:171], 0
	v_mfma_f32_16x16x32_bf16 v[40:43], v[112:115], v[168:171], 0
	v_mfma_f32_16x16x32_bf16 v[28:31], v[88:91], v[176:179], 0
	v_mfma_f32_16x16x32_bf16 v[24:27], v[112:115], v[176:179], 0
	v_mfma_f32_16x16x32_bf16 v[12:15], v[88:91], v[184:187], 0
	v_mfma_f32_16x16x32_bf16 v[8:11], v[112:115], v[184:187], 0
	v_mfma_f32_16x16x32_bf16 v[60:63], v[100:103], v[156:159], v[60:63]
	v_mfma_f32_16x16x32_bf16 v[56:59], v[124:127], v[156:159], v[56:59]
	v_mfma_f32_16x16x32_bf16 v[44:47], v[100:103], v[172:175], v[44:47]
	v_mfma_f32_16x16x32_bf16 v[40:43], v[124:127], v[172:175], v[40:43]
	v_mfma_f32_16x16x32_bf16 v[28:31], v[100:103], v[180:183], v[28:31]
	v_mfma_f32_16x16x32_bf16 v[24:27], v[124:127], v[180:183], v[24:27]
	v_mfma_f32_16x16x32_bf16 v[12:15], v[100:103], v[188:191], v[12:15]
	v_mfma_f32_16x16x32_bf16 v[8:11], v[124:127], v[188:191], v[8:11]
	s_setprio 0
	s_setprio 1
	v_mfma_f32_16x16x32_bf16 v[52:55], v[128:131], v[152:155], 0
	v_mfma_f32_16x16x32_bf16 v[48:51], v[136:139], v[152:155], 0
	v_mfma_f32_16x16x32_bf16 v[36:39], v[128:131], v[168:171], 0
	v_mfma_f32_16x16x32_bf16 v[32:35], v[136:139], v[168:171], 0
	v_mfma_f32_16x16x32_bf16 v[20:23], v[128:131], v[176:179], 0
	v_mfma_f32_16x16x32_bf16 v[16:19], v[136:139], v[176:179], 0
	v_mfma_f32_16x16x32_bf16 v[4:7], v[128:131], v[184:187], 0
	v_mfma_f32_16x16x32_bf16 v[0:3], v[136:139], v[184:187], 0
	v_mfma_f32_16x16x32_bf16 v[52:55], v[132:135], v[156:159], v[52:55]
	v_mfma_f32_16x16x32_bf16 v[48:51], v[144:147], v[156:159], v[48:51]
	v_mfma_f32_16x16x32_bf16 v[36:39], v[132:135], v[172:175], v[36:39]
	v_mfma_f32_16x16x32_bf16 v[32:35], v[144:147], v[172:175], v[32:35]
	v_mfma_f32_16x16x32_bf16 v[20:23], v[132:135], v[180:183], v[20:23]
	v_mfma_f32_16x16x32_bf16 v[16:19], v[144:147], v[180:183], v[16:19]
	v_mfma_f32_16x16x32_bf16 v[4:7], v[132:135], v[188:191], v[4:7]
	v_mfma_f32_16x16x32_bf16 v[0:3], v[144:147], v[188:191], v[0:3]
	s_setprio 0
	s_barrier
	s_branch .Ldown_mid
.LBB0_654:
	s_add_u32 s38, s34, 0x6000
	s_addc_u32 s39, s35, 0
	s_cmp_eq_u32 s27, 40
	s_cselect_b32 s42, s56, s38
	s_cselect_b32 s43, s57, s39
	s_cselect_b32 s40, s60, s2
	s_cselect_b32 s41, s61, s3
	s_add_u32 s38, s42, 0x8000
	s_addc_u32 s39, s43, 0
	s_add_i32 s44, 0, 0x10000
	s_add_i32 s46, 0, 0x14000
	v_add_u32_e32 v124, s44, v248
	v_add_u32_e32 v144, s46, v248
	ds_read_b128 v[88:91], v124
	ds_read_b128 v[100:103], v124 offset:1024
	ds_read_b128 v[112:115], v124 offset:2048
	ds_read_b128 v[124:127], v124 offset:3072
	ds_read_b128 v[128:131], v144
	ds_read_b128 v[132:135], v144 offset:1024
	ds_read_b128 v[136:139], v144 offset:2048
	ds_read_b128 v[144:147], v144 offset:3072
	s_add_i32 m0, s95, 0xc000
	ds_read_b128 v[152:155], v249
	ds_read_b128 v[156:159], v249 offset:1024
	ds_read_b128 v[168:171], v249 offset:2048
	ds_read_b128 v[172:175], v249 offset:3072
	ds_read_b128 v[176:179], v249 offset:4096
	ds_read_b128 v[180:183], v249 offset:5120
	ds_read_b128 v[184:187], v249 offset:6144
	ds_read_b128 v[188:191], v249 offset:7168
	global_load_lds_dwordx4 v224, s[34:35]
	s_add_i32 m0, s95, 0xe000
	s_nop 0
	global_load_lds_dwordx4 v226, s[34:35]
	s_waitcnt vmcnt(8)
	s_waitcnt lgkmcnt(0)
	s_barrier
	s_setprio 1
	s_waitcnt lgkmcnt(0)
	v_mfma_f32_16x16x32_bf16 v[164:167], v[88:91], v[152:155], v[164:167]
	v_mfma_f32_16x16x32_bf16 v[160:163], v[112:115], v[152:155], v[160:163]
	v_mfma_f32_16x16x32_bf16 v[120:123], v[88:91], v[168:171], v[120:123]
	v_mfma_f32_16x16x32_bf16 v[116:119], v[112:115], v[168:171], v[116:119]
	v_mfma_f32_16x16x32_bf16 v[96:99], v[88:91], v[176:179], v[96:99]
	v_mfma_f32_16x16x32_bf16 v[92:95], v[112:115], v[176:179], v[92:95]
	v_mfma_f32_16x16x32_bf16 v[76:79], v[88:91], v[184:187], v[76:79]
	v_mfma_f32_16x16x32_bf16 v[72:75], v[112:115], v[184:187], v[72:75]
	v_mfma_f32_16x16x32_bf16 v[164:167], v[100:103], v[156:159], v[164:167]
	v_mfma_f32_16x16x32_bf16 v[160:163], v[124:127], v[156:159], v[160:163]
	v_mfma_f32_16x16x32_bf16 v[120:123], v[100:103], v[172:175], v[120:123]
	v_mfma_f32_16x16x32_bf16 v[116:119], v[124:127], v[172:175], v[116:119]
	v_mfma_f32_16x16x32_bf16 v[96:99], v[100:103], v[180:183], v[96:99]
	v_mfma_f32_16x16x32_bf16 v[92:95], v[124:127], v[180:183], v[92:95]
	v_mfma_f32_16x16x32_bf16 v[76:79], v[100:103], v[188:191], v[76:79]
	v_mfma_f32_16x16x32_bf16 v[72:75], v[124:127], v[188:191], v[72:75]
	s_setprio 0
	s_setprio 1
	v_mfma_f32_16x16x32_bf16 v[148:151], v[128:131], v[152:155], v[148:151]
	v_mfma_f32_16x16x32_bf16 v[140:143], v[136:139], v[152:155], v[140:143]
	v_mfma_f32_16x16x32_bf16 v[108:111], v[128:131], v[168:171], v[108:111]
	v_mfma_f32_16x16x32_bf16 v[104:107], v[136:139], v[168:171], v[104:107]
	v_mfma_f32_16x16x32_bf16 v[84:87], v[128:131], v[176:179], v[84:87]
	v_mfma_f32_16x16x32_bf16 v[80:83], v[136:139], v[176:179], v[80:83]
	v_mfma_f32_16x16x32_bf16 v[68:71], v[128:131], v[184:187], v[68:71]
	v_mfma_f32_16x16x32_bf16 v[64:67], v[136:139], v[184:187], v[64:67]
	v_mfma_f32_16x16x32_bf16 v[148:151], v[132:135], v[156:159], v[148:151]
	v_mfma_f32_16x16x32_bf16 v[140:143], v[144:147], v[156:159], v[140:143]
	v_mfma_f32_16x16x32_bf16 v[108:111], v[132:135], v[172:175], v[108:111]
	v_mfma_f32_16x16x32_bf16 v[104:107], v[144:147], v[172:175], v[104:107]
	v_mfma_f32_16x16x32_bf16 v[84:87], v[132:135], v[180:183], v[84:87]
	v_mfma_f32_16x16x32_bf16 v[80:83], v[144:147], v[180:183], v[80:83]
	v_mfma_f32_16x16x32_bf16 v[68:71], v[132:135], v[188:191], v[68:71]
	v_mfma_f32_16x16x32_bf16 v[64:67], v[144:147], v[188:191], v[64:67]
	s_setprio 0
	s_barrier
	s_add_i32 s44, s44, s94
	s_mov_b32 m0, s44
	ds_read_b128 v[152:155], v249 offset:16384
	ds_read_b128 v[156:159], v249 offset:17408
	ds_read_b128 v[168:171], v249 offset:18432
	ds_read_b128 v[172:175], v249 offset:19456
	ds_read_b128 v[176:179], v249 offset:20480
	ds_read_b128 v[180:183], v249 offset:21504
	ds_read_b128 v[184:187], v249 offset:22528
	ds_read_b128 v[188:191], v249 offset:23552
	global_load_lds_dwordx4 v208, s[40:41]
	s_add_i32 m0, s44, 0x2000
	s_add_u32 s44, s40, 0xb0000
	s_addc_u32 s45, s41, 0
	s_add_i32 s46, s46, s94
	global_load_lds_dwordx4 v222, s[40:41]
	s_mov_b32 m0, s46
	s_nop 0
	global_load_lds_dwordx4 v208, s[44:45]
	s_add_i32 m0, s46, 0x2000
	s_nop 0
	global_load_lds_dwordx4 v222, s[44:45]
	s_mov_b32 m0, s95
	s_nop 0
	global_load_lds_dwordx4 v218, s[42:43]
	s_mov_b32 m0, s18
	s_nop 0
	global_load_lds_dwordx4 v220, s[42:43]
	s_waitcnt vmcnt(8)
	s_waitcnt lgkmcnt(0)
	s_barrier
	s_setprio 1
	s_waitcnt lgkmcnt(0)
	v_mfma_f32_16x16x32_bf16 v[60:63], v[88:91], v[152:155], v[60:63]
	v_mfma_f32_16x16x32_bf16 v[56:59], v[112:115], v[152:155], v[56:59]
	v_mfma_f32_16x16x32_bf16 v[44:47], v[88:91], v[168:171], v[44:47]
	v_mfma_f32_16x16x32_bf16 v[40:43], v[112:115], v[168:171], v[40:43]
	v_mfma_f32_16x16x32_bf16 v[28:31], v[88:91], v[176:179], v[28:31]
	v_mfma_f32_16x16x32_bf16 v[24:27], v[112:115], v[176:179], v[24:27]
	v_mfma_f32_16x16x32_bf16 v[12:15], v[88:91], v[184:187], v[12:15]
	v_mfma_f32_16x16x32_bf16 v[8:11], v[112:115], v[184:187], v[8:11]
	v_mfma_f32_16x16x32_bf16 v[60:63], v[100:103], v[156:159], v[60:63]
	v_mfma_f32_16x16x32_bf16 v[56:59], v[124:127], v[156:159], v[56:59]
	v_mfma_f32_16x16x32_bf16 v[44:47], v[100:103], v[172:175], v[44:47]
	v_mfma_f32_16x16x32_bf16 v[40:43], v[124:127], v[172:175], v[40:43]
	v_mfma_f32_16x16x32_bf16 v[28:31], v[100:103], v[180:183], v[28:31]
	v_mfma_f32_16x16x32_bf16 v[24:27], v[124:127], v[180:183], v[24:27]
	v_mfma_f32_16x16x32_bf16 v[12:15], v[100:103], v[188:191], v[12:15]
	v_mfma_f32_16x16x32_bf16 v[8:11], v[124:127], v[188:191], v[8:11]
	s_setprio 0
	s_setprio 1
	v_mfma_f32_16x16x32_bf16 v[52:55], v[128:131], v[152:155], v[52:55]
	v_mfma_f32_16x16x32_bf16 v[48:51], v[136:139], v[152:155], v[48:51]
	v_mfma_f32_16x16x32_bf16 v[36:39], v[128:131], v[168:171], v[36:39]
	v_mfma_f32_16x16x32_bf16 v[32:35], v[136:139], v[168:171], v[32:35]
	v_mfma_f32_16x16x32_bf16 v[20:23], v[128:131], v[176:179], v[20:23]
	v_mfma_f32_16x16x32_bf16 v[16:19], v[136:139], v[176:179], v[16:19]
	v_mfma_f32_16x16x32_bf16 v[4:7], v[128:131], v[184:187], v[4:7]
	v_mfma_f32_16x16x32_bf16 v[0:3], v[136:139], v[184:187], v[0:3]
	v_mfma_f32_16x16x32_bf16 v[52:55], v[132:135], v[156:159], v[52:55]
	v_mfma_f32_16x16x32_bf16 v[48:51], v[144:147], v[156:159], v[48:51]
	v_mfma_f32_16x16x32_bf16 v[36:39], v[132:135], v[172:175], v[36:39]
	v_mfma_f32_16x16x32_bf16 v[32:35], v[144:147], v[172:175], v[32:35]
	v_mfma_f32_16x16x32_bf16 v[20:23], v[132:135], v[180:183], v[20:23]
	v_mfma_f32_16x16x32_bf16 v[16:19], v[144:147], v[180:183], v[16:19]
	v_mfma_f32_16x16x32_bf16 v[4:7], v[132:135], v[188:191], v[4:7]
	v_mfma_f32_16x16x32_bf16 v[0:3], v[144:147], v[188:191], v[0:3]
	s_setprio 0
	s_barrier
.Ldown_mid:
	s_add_i32 s44, 0, 0x18000
	s_add_i32 s45, 0, 0x1c000
	v_add_u32_e32 v124, s44, v248
	v_add_u32_e32 v144, s45, v248
	ds_read_b128 v[88:91], v124
	ds_read_b128 v[100:103], v124 offset:1024
	ds_read_b128 v[112:115], v124 offset:2048
	ds_read_b128 v[124:127], v124 offset:3072
	ds_read_b128 v[128:131], v144
	ds_read_b128 v[132:135], v144 offset:1024
	ds_read_b128 v[136:139], v144 offset:2048
	ds_read_b128 v[144:147], v144 offset:3072
	s_add_u32 s42, s42, 0x2000
	s_addc_u32 s43, s43, 0
	s_mov_b32 m0, s19
	ds_read_b128 v[152:155], v249 offset:32768
	ds_read_b128 v[156:159], v249 offset:33792
	ds_read_b128 v[168:171], v249 offset:34816
	ds_read_b128 v[172:175], v249 offset:35840
	ds_read_b128 v[176:179], v249 offset:36864
	ds_read_b128 v[180:183], v249 offset:37888
	ds_read_b128 v[184:187], v249 offset:38912
	ds_read_b128 v[188:191], v249 offset:39936
	global_load_lds_dwordx4 v218, s[42:43]
	s_mov_b32 m0, s66
	s_nop 0
	global_load_lds_dwordx4 v220, s[42:43]
	s_waitcnt vmcnt(8)
	s_waitcnt lgkmcnt(0)
	s_barrier
	s_setprio 1
	s_waitcnt lgkmcnt(0)
	v_mfma_f32_16x16x32_bf16 v[164:167], v[88:91], v[152:155], v[164:167]
	v_mfma_f32_16x16x32_bf16 v[160:163], v[112:115], v[152:155], v[160:163]
	v_mfma_f32_16x16x32_bf16 v[120:123], v[88:91], v[168:171], v[120:123]
	v_mfma_f32_16x16x32_bf16 v[116:119], v[112:115], v[168:171], v[116:119]
	v_mfma_f32_16x16x32_bf16 v[96:99], v[88:91], v[176:179], v[96:99]
	v_mfma_f32_16x16x32_bf16 v[92:95], v[112:115], v[176:179], v[92:95]
	v_mfma_f32_16x16x32_bf16 v[76:79], v[88:91], v[184:187], v[76:79]
	v_mfma_f32_16x16x32_bf16 v[72:75], v[112:115], v[184:187], v[72:75]
	v_mfma_f32_16x16x32_bf16 v[164:167], v[100:103], v[156:159], v[164:167]
	v_mfma_f32_16x16x32_bf16 v[160:163], v[124:127], v[156:159], v[160:163]
	v_mfma_f32_16x16x32_bf16 v[120:123], v[100:103], v[172:175], v[120:123]
	v_mfma_f32_16x16x32_bf16 v[116:119], v[124:127], v[172:175], v[116:119]
	v_mfma_f32_16x16x32_bf16 v[96:99], v[100:103], v[180:183], v[96:99]
	v_mfma_f32_16x16x32_bf16 v[92:95], v[124:127], v[180:183], v[92:95]
	v_mfma_f32_16x16x32_bf16 v[76:79], v[100:103], v[188:191], v[76:79]
	v_mfma_f32_16x16x32_bf16 v[72:75], v[124:127], v[188:191], v[72:75]
	s_setprio 0
	s_setprio 1
	v_mfma_f32_16x16x32_bf16 v[148:151], v[128:131], v[152:155], v[148:151]
	v_mfma_f32_16x16x32_bf16 v[140:143], v[136:139], v[152:155], v[140:143]
	v_mfma_f32_16x16x32_bf16 v[108:111], v[128:131], v[168:171], v[108:111]
	v_mfma_f32_16x16x32_bf16 v[104:107], v[136:139], v[168:171], v[104:107]
	v_mfma_f32_16x16x32_bf16 v[84:87], v[128:131], v[176:179], v[84:87]
	v_mfma_f32_16x16x32_bf16 v[80:83], v[136:139], v[176:179], v[80:83]
	v_mfma_f32_16x16x32_bf16 v[68:71], v[128:131], v[184:187], v[68:71]
	v_mfma_f32_16x16x32_bf16 v[64:67], v[136:139], v[184:187], v[64:67]
	v_mfma_f32_16x16x32_bf16 v[148:151], v[132:135], v[156:159], v[148:151]
	v_mfma_f32_16x16x32_bf16 v[140:143], v[144:147], v[156:159], v[140:143]
	v_mfma_f32_16x16x32_bf16 v[108:111], v[132:135], v[172:175], v[108:111]
	v_mfma_f32_16x16x32_bf16 v[104:107], v[144:147], v[172:175], v[104:107]
	v_mfma_f32_16x16x32_bf16 v[84:87], v[132:135], v[180:183], v[84:87]
	v_mfma_f32_16x16x32_bf16 v[80:83], v[144:147], v[180:183], v[80:83]
	v_mfma_f32_16x16x32_bf16 v[68:71], v[132:135], v[188:191], v[68:71]
	v_mfma_f32_16x16x32_bf16 v[64:67], v[144:147], v[188:191], v[64:67]
	s_setprio 0
	s_barrier
	s_add_i32 s42, s44, s94
	s_add_u32 s98, s40, 0x80
	s_addc_u32 s99, s41, 0
	s_mov_b32 m0, s42
	ds_read_b128 v[152:155], v249 offset:49152
	ds_read_b128 v[156:159], v249 offset:50176
	ds_read_b128 v[168:171], v249 offset:51200
	ds_read_b128 v[172:175], v249 offset:52224
	ds_read_b128 v[176:179], v249 offset:53248
	ds_read_b128 v[180:183], v249 offset:54272
	ds_read_b128 v[184:187], v249 offset:55296
	ds_read_b128 v[188:191], v249 offset:56320
	global_load_lds_dwordx4 v208, s[98:99]
	s_add_i32 m0, s42, 0x2000
	s_add_u32 s40, s40, 0xb0080
	s_addc_u32 s41, s41, 0
	s_add_i32 s42, s45, s94
	global_load_lds_dwordx4 v222, s[98:99]
	s_mov_b32 m0, s42
	s_nop 0
	global_load_lds_dwordx4 v208, s[40:41]
	s_add_i32 m0, s42, 0x2000
	s_nop 0
	global_load_lds_dwordx4 v222, s[40:41]
	s_mov_b32 m0, s72
	s_nop 0
	global_load_lds_dwordx4 v218, s[38:39]
	s_mov_b32 m0, s73
	s_nop 0
	global_load_lds_dwordx4 v220, s[38:39]
	s_waitcnt vmcnt(8)
	s_waitcnt lgkmcnt(0)
	s_barrier
	s_setprio 1
	s_waitcnt lgkmcnt(0)
	v_mfma_f32_16x16x32_bf16 v[60:63], v[88:91], v[152:155], v[60:63]
	v_mfma_f32_16x16x32_bf16 v[56:59], v[112:115], v[152:155], v[56:59]
	v_mfma_f32_16x16x32_bf16 v[44:47], v[88:91], v[168:171], v[44:47]
	v_mfma_f32_16x16x32_bf16 v[40:43], v[112:115], v[168:171], v[40:43]
	v_mfma_f32_16x16x32_bf16 v[28:31], v[88:91], v[176:179], v[28:31]
	v_mfma_f32_16x16x32_bf16 v[24:27], v[112:115], v[176:179], v[24:27]
	v_mfma_f32_16x16x32_bf16 v[12:15], v[88:91], v[184:187], v[12:15]
	v_mfma_f32_16x16x32_bf16 v[8:11], v[112:115], v[184:187], v[8:11]
	v_mfma_f32_16x16x32_bf16 v[60:63], v[100:103], v[156:159], v[60:63]
	v_mfma_f32_16x16x32_bf16 v[56:59], v[124:127], v[156:159], v[56:59]
	v_mfma_f32_16x16x32_bf16 v[44:47], v[100:103], v[172:175], v[44:47]
	v_mfma_f32_16x16x32_bf16 v[40:43], v[124:127], v[172:175], v[40:43]
	v_mfma_f32_16x16x32_bf16 v[28:31], v[100:103], v[180:183], v[28:31]
	v_mfma_f32_16x16x32_bf16 v[24:27], v[124:127], v[180:183], v[24:27]
	v_mfma_f32_16x16x32_bf16 v[12:15], v[100:103], v[188:191], v[12:15]
	v_mfma_f32_16x16x32_bf16 v[8:11], v[124:127], v[188:191], v[8:11]
	s_setprio 0
	s_setprio 1
	v_mfma_f32_16x16x32_bf16 v[52:55], v[128:131], v[152:155], v[52:55]
	v_mfma_f32_16x16x32_bf16 v[48:51], v[136:139], v[152:155], v[48:51]
	v_mfma_f32_16x16x32_bf16 v[36:39], v[128:131], v[168:171], v[36:39]
	v_mfma_f32_16x16x32_bf16 v[32:35], v[136:139], v[168:171], v[32:35]
	v_mfma_f32_16x16x32_bf16 v[20:23], v[128:131], v[176:179], v[20:23]
	v_mfma_f32_16x16x32_bf16 v[16:19], v[136:139], v[176:179], v[16:19]
	v_mfma_f32_16x16x32_bf16 v[4:7], v[128:131], v[184:187], v[4:7]
	v_mfma_f32_16x16x32_bf16 v[0:3], v[136:139], v[184:187], v[0:3]
	v_mfma_f32_16x16x32_bf16 v[52:55], v[132:135], v[156:159], v[52:55]
	v_mfma_f32_16x16x32_bf16 v[48:51], v[144:147], v[156:159], v[48:51]
	v_mfma_f32_16x16x32_bf16 v[36:39], v[132:135], v[172:175], v[36:39]
	v_mfma_f32_16x16x32_bf16 v[32:35], v[144:147], v[172:175], v[32:35]
	v_mfma_f32_16x16x32_bf16 v[20:23], v[132:135], v[180:183], v[20:23]
	v_mfma_f32_16x16x32_bf16 v[16:19], v[144:147], v[180:183], v[16:19]
	v_mfma_f32_16x16x32_bf16 v[4:7], v[132:135], v[188:191], v[4:7]
	v_mfma_f32_16x16x32_bf16 v[0:3], v[144:147], v[188:191], v[0:3]
	s_setprio 0
	s_barrier
	s_add_i32 s27, s27, 2
	s_add_u32 s2, s2, 0x100
	s_addc_u32 s3, s3, 0
	s_add_u32 s34, s34, 0x10000
	s_addc_u32 s35, s35, 0
	s_cmp_gt_u32 s27, 41
	s_cbranch_scc0 .LBB0_654
	s_and_b64 vcc, exec, s[76:77]
	s_cbranch_vccz .LBB0_657
	s_barrier
